# sparse attention unit loop no longer waits for the previous unit's output store at the top of a unit
# speedup vs baseline: 1.0051x; 1.0005x over previous
; #define LAS __attribute__((address_space(3)))
; __device__ __forceinline__ void sparse_unit7(const bf16_t* QKV, const unsigned char* K8, const unsigned char* V8, const int (&selv)[4], bf16_t* OB, LAS unsigned char* wl, int t, int h, int lane) {
;     LAS int* wsel = (LAS int*)wl; LAS unsigned* otw = (LAS unsigned*)(wl + 1024); LAS float* ptw = (LAS float*)(wl + 2048);
;     const int n16 = lane & 15, slab = lane >> 4, half = lane >> 5, l4 = (lane & 31) * 4;
;     const bf16_t* qrow = QKV + (size_t)t * QKVW + COL_BQ + h * 128 + 16 * slab;
;     long qa[4];
; #pragma unroll
;     for (int ks = 0; ks < 4; ++ks) { const u32x4 raw = *(const u32x4*)(qrow + 8 * (ks & 1) + 64 * (ks >> 1)); const unsigned w[4] = {raw.x, raw.y, raw.z, raw.w}; float x[8];
; #pragma unroll
;         for (int i = 0; i < 4; ++i) { x[2 * i] = bf2f(w[i] & 0xffffu); x[2 * i + 1] = __builtin_bit_cast(float, w[i] & 0xffff0000u); }
;         const u32x2 f = to_fp8x8(x); qa[ks] = (long)(((unsigned long long)f.y << 32) | f.x); }
;     const unsigned char* K8h = K8 + h * 128; const unsigned char* V8h = V8 + h * 128;
;     const int n = min(256, t + 1), ns = (n + 63) >> 6;
; #pragma unroll
;     for (int s = 0; s < 4; ++s) { const int j = 64 * s + lane; const int id = (j < n) ? selv[s] : 0; wsel[j] = id; otw[j] = (unsigned)id * 1024u; }
; __global__ void __launch_bounds__(NTHREADS, 2) mega(Args a) {
;     ...
;                 const int h = blockIdx.x & 7, qg = (blockIdx.x >> 3) * NWAVES + wave, nqg = ((G + 7) >> 3) * NWAVES;
;                 for (int u = gw; u < SEQ * 4; u += NGW) dilated_merge(OG, LSE, OA, u >> 2, u & 3, lane);
;                 for (int rep = 0; rep < REP_SP; ++rep)
;                 if ((G & 7) == 0) { int seln[4];
; #pragma unroll
;                     for (int s = 0; s < 4; ++s) seln[s] = (int)SEL[(size_t)min(qg, SEQ - 1) * 256 + 64 * s + lane];
;                     for (int t = qg; t < SEQ; t += nqg) { int selc[4];
; #pragma unroll
;                         for (int s = 0; s < 4; ++s) selc[s] = seln[s];
;                         const int tn = min(t + nqg, SEQ - 1);
; #pragma unroll
;                         for (int s = 0; s < 4; ++s) seln[s] = (int)SEL[(size_t)tn * 256 + 64 * s + lane];
;                         sparse_unit7(QKV, K8, V8, selc, OB, lds + wave * 4096, t, h, lane); } }
.LBB0_160:
.LBB0_161:
	v_readlane_b32 s0, v251, 0
	v_readlane_b32 s1, v250, 18
	s_nop 3
	s_and_b32 s4, s0, 7
	s_and_b32 s5, s0, -8
	s_add_i32 s34, s5, s1
	s_add_i32 s48, s94, 7
	s_and_b32 s48, s48, -8
	s_add_u32 s38, s90, 0x28600000
	s_addc_u32 s39, s91, 0
	s_lshl_b32 s5, s4, 8
	s_add_u32 s5, s5, 0x12302400
	s_add_u32 s40, s90, s5
	s_addc_u32 s41, s91, 0
	s_lshl_b32 s5, s4, 21
	s_add_u32 s0, s5, 0x3cf00000
	s_add_u32 s42, s90, s0
	s_addc_u32 s43, s91, 0
	s_add_u32 s0, s5, 0x3df00000
	s_add_u32 s44, s90, s0
	s_addc_u32 s45, s91, 0
	s_lshl_b32 s5, s4, 8
	s_add_u32 s0, s5, 0x29e00000
	s_add_u32 s46, s90, s0
	s_addc_u32 s47, s91, 0
	s_lshl_b32 s0, s1, 13
	v_and_b32_e32 v218, 15, v182
	v_lshrrev_b32_e32 v219, 4, v182
	v_and_b32_e32 v246, 7, v182
	v_lshrrev_b32_e32 v247, 3, v182
	v_lshlrev_b32_e32 v200, 6, v247
	v_lshlrev_b32_e32 v201, 5, v219
	v_xor_b32_e32 v248, v246, v247
	v_lshlrev_b32_e32 v202, 4, v248
	v_lshlrev_b32_e32 v203, 4, v246
	v_lshl_add_u32 v224, v182, 4, s0
	v_and_b32_e32 v248, 7, v218
	v_lshrrev_b32_e32 v249, 3, v218
	v_lshlrev_b32_e32 v227, 4, v249
	v_lshlrev_b32_e32 v225, 10, v249
	v_lshl_add_u32 v225, v248, 7, v225
	v_add_u32_e32 v225, s0, v225
	v_xor_b32_e32 v217, v219, v248
	v_xor_b32_e32 v226, 4, v217
	v_lshl_add_u32 v226, v226, 4, v225
	v_lshl_add_u32 v225, v217, 4, v225
	v_lshlrev_b32_e32 v217, 5, v248
	v_lshl_add_u32 v217, v219, 3, v217
	v_sub_u32_e32 v216, v217, v161
	v_lshlrev_b32_e32 v216, 1, v216
	v_add_u32_e32 v217, v217, v249
	v_lshlrev_b32_e32 v248, 4, v218
	v_lshl_add_u32 v248, v219, 2, v248
	v_lshrrev_b32_e32 v249, 1, v218
	v_lshl_add_u32 v248, v249, 2, v248
	v_lshlrev_b32_e32 v213, 2, v248
	s_add_i32 s1, s0, 0x1000
	v_add_u32_e32 v213, s1, v213
	v_mul_u32_u24_e32 v214, 0x90, v247
	v_add_u32_e32 v214, s1, v214
	v_lshlrev_b32_e32 v215, 5, v246
	v_lshl_add_u32 v215, v219, 3, v215
	v_cmp_eq_u32_e64 s[8:9], 0, v219
	v_cmp_eq_u32_e64 s[10:11], 1, v219
	v_cmp_eq_u32_e64 s[16:17], 2, v219
	v_cmp_eq_u32_e64 s[22:23], 3, v219
	s_lshl_b32 s0, s34, 9
	s_add_u32 s0, s38, s0
	s_addc_u32 s1, s39, 0
	s_mul_i32 s4, s34, 0x3c00
	s_add_u32 s4, s40, s4
	s_addc_u32 s5, s41, 0
	global_load_dwordx4 v[96:99], v200, s[0:1]
	global_load_dwordx4 v[100:103], v200, s[0:1] offset:16
	global_load_dwordx4 v[104:107], v200, s[0:1] offset:32
	global_load_dwordx4 v[108:111], v200, s[0:1] offset:48
	global_load_dwordx4 v[220:223], v216, s[0:1]
	global_load_dwordx4 v[230:233], v201, s[4:5]
	global_load_dwordx4 v[234:237], v201, s[4:5] offset:16
	global_load_dwordx4 v[238:241], v201, s[4:5] offset:128
	global_load_dwordx4 v[242:245], v201, s[4:5] offset:144
	s_waitcnt vmcnt(0)
	s_nop 0
.Lsp_unit:
	s_waitcnt vmcnt(1)
	s_add_i32 s98, s34, 1
	s_min_i32 s98, s98, 0x100
	v_and_b32_e32 v218, 0x3fff, v96
	v_lshl_add_u32 v218, v218, 7, v202
	global_load_dwordx4 v[0:3], v218, s[42:43]
	v_bfe_u32 v218, v96, 16, 14
	v_lshl_add_u32 v218, v218, 7, v202
	global_load_dwordx4 v[4:7], v218, s[42:43]
	v_and_b32_e32 v218, 0x3fff, v97
	v_lshl_add_u32 v218, v218, 7, v202
	global_load_dwordx4 v[8:11], v218, s[42:43]
	v_bfe_u32 v218, v97, 16, 14
	v_lshl_add_u32 v218, v218, 7, v202
	global_load_dwordx4 v[12:15], v218, s[42:43]
	v_and_b32_e32 v218, 0x3fff, v98
	v_lshl_add_u32 v218, v218, 7, v202
	global_load_dwordx4 v[16:19], v218, s[42:43]
	v_bfe_u32 v218, v98, 16, 14
	v_lshl_add_u32 v218, v218, 7, v202
	global_load_dwordx4 v[20:23], v218, s[42:43]
	v_and_b32_e32 v218, 0x3fff, v99
	v_lshl_add_u32 v218, v218, 7, v202
	global_load_dwordx4 v[24:27], v218, s[42:43]
	v_bfe_u32 v218, v99, 16, 14
	v_lshl_add_u32 v218, v218, 7, v202
	global_load_dwordx4 v[28:31], v218, s[42:43]
	v_and_b32_e32 v218, 0x3fff, v100
	v_lshl_add_u32 v218, v218, 7, v202
	global_load_dwordx4 v[32:35], v218, s[42:43]
	v_bfe_u32 v218, v100, 16, 14
	v_lshl_add_u32 v218, v218, 7, v202
	global_load_dwordx4 v[36:39], v218, s[42:43]
	v_and_b32_e32 v218, 0x3fff, v101
	v_lshl_add_u32 v218, v218, 7, v202
	global_load_dwordx4 v[40:43], v218, s[42:43]
	v_bfe_u32 v218, v101, 16, 14
	v_lshl_add_u32 v218, v218, 7, v202
	global_load_dwordx4 v[44:47], v218, s[42:43]
	v_and_b32_e32 v218, 0x3fff, v102
	v_lshl_add_u32 v218, v218, 7, v202
	global_load_dwordx4 v[48:51], v218, s[42:43]
	v_bfe_u32 v218, v102, 16, 14
	v_lshl_add_u32 v218, v218, 7, v202
	global_load_dwordx4 v[52:55], v218, s[42:43]
	v_and_b32_e32 v218, 0x3fff, v103
	v_lshl_add_u32 v218, v218, 7, v202
	global_load_dwordx4 v[56:59], v218, s[42:43]
	v_bfe_u32 v218, v103, 16, 14
	v_lshl_add_u32 v218, v218, 7, v202
	global_load_dwordx4 v[60:63], v218, s[42:43]
	v_and_b32_e32 v218, 0x3fff, v104
	v_lshl_add_u32 v218, v218, 7, v202
	global_load_dwordx4 v[64:67], v218, s[42:43]
	v_bfe_u32 v218, v104, 16, 14
	v_lshl_add_u32 v218, v218, 7, v202
	global_load_dwordx4 v[68:71], v218, s[42:43]
	v_and_b32_e32 v218, 0x3fff, v105
	v_lshl_add_u32 v218, v218, 7, v202
	global_load_dwordx4 v[72:75], v218, s[42:43]
	v_bfe_u32 v218, v105, 16, 14
	v_lshl_add_u32 v218, v218, 7, v202
	global_load_dwordx4 v[76:79], v218, s[42:43]
	v_and_b32_e32 v218, 0x3fff, v106
	v_lshl_add_u32 v218, v218, 7, v202
	global_load_dwordx4 v[80:83], v218, s[42:43]
	v_bfe_u32 v218, v106, 16, 14
	v_lshl_add_u32 v218, v218, 7, v202
	global_load_dwordx4 v[84:87], v218, s[42:43]
	v_and_b32_e32 v218, 0x3fff, v107
	v_lshl_add_u32 v218, v218, 7, v202
	global_load_dwordx4 v[88:91], v218, s[42:43]
	v_bfe_u32 v218, v107, 16, 14
	v_lshl_add_u32 v218, v218, 7, v202
	global_load_dwordx4 v[92:95], v218, s[42:43]
	v_and_b32_e32 v112, 0x3fff, v108
	v_lshl_add_u32 v112, v112, 7, v202
	v_bfe_u32 v113, v108, 16, 14
	v_lshl_add_u32 v113, v113, 7, v202
	v_and_b32_e32 v114, 0x3fff, v109
	v_lshl_add_u32 v114, v114, 7, v202
; __device__ __forceinline__ void s8_issue_k(long (&kf)[16], const unsigned char* K8h, LAS const int* wsel, int j0, int n16, int slab) {
; #pragma unroll
;     for (int g = 0; g < 4; ++g) { const unsigned char* kp = K8h + (size_t)wsel[j0 + 16 * g + n16] * 1024 + 16 * slab;
;         const u32x4 lo = *(const u32x4*)kp, hi = *(const u32x4*)(kp + 64);
;         kf[g * 4 + 0] = (long)(((unsigned long long)lo.y << 32) | lo.x); kf[g * 4 + 1] = (long)(((unsigned long long)lo.w << 32) | lo.z);
;         kf[g * 4 + 2] = (long)(((unsigned long long)hi.y << 32) | hi.x); kf[g * 4 + 3] = (long)(((unsigned long long)hi.w << 32) | hi.z); }
; }
; template <int Q> __device__ __forceinline__ void s9_issue_v(unsigned (&vv)[8], const unsigned char* V8h, LAS const unsigned* otw, int half, int l4) {
; #pragma unroll
;     for (int u2 = 0; u2 < 8; ++u2) vv[u2] = *(const unsigned*)(V8h + (otw[2 * (Q * 8 + u2) + half] | (unsigned)l4));
; }
; template <int Q> __device__ __forceinline__ void s9_pv(const unsigned (&vv)[8], LAS const float* ptw, int half, f32x2_t& oa, f32x2_t& ob) {
; #pragma unroll
;     for (int u2 = 0; u2 < 8; ++u2) { const float p = ptw[2 * (Q * 8 + u2) + half];
;         oa = __builtin_amdgcn_cvt_pk_f32_fp8((int)vv[u2], false) * p + oa; ob = __builtin_amdgcn_cvt_pk_f32_fp8((int)vv[u2], true) * p + ob; }
; }
; __device__ __forceinline__ void sparse_unit7(const bf16_t* QKV, const unsigned char* K8, const unsigned char* V8, const int (&selv)[4], bf16_t* OB, LAS unsigned char* wl, int t, int h, int lane) {
;     LAS int* wsel = (LAS int*)wl; LAS unsigned* otw = (LAS unsigned*)(wl + 1024); LAS float* ptw = (LAS float*)(wl + 2048);
;     const int n16 = lane & 15, slab = lane >> 4, half = lane >> 5, l4 = (lane & 31) * 4;
;     const bf16_t* qrow = QKV + (size_t)t * QKVW + COL_BQ + h * 128 + 16 * slab;
;     long qa[4];
; #pragma unroll
;     for (int ks = 0; ks < 4; ++ks) { const u32x4 raw = *(const u32x4*)(qrow + 8 * (ks & 1) + 64 * (ks >> 1)); const unsigned w[4] = {raw.x, raw.y, raw.z, raw.w}; float x[8];
; #pragma unroll
;         for (int i = 0; i < 4; ++i) { x[2 * i] = bf2f(w[i] & 0xffffu); x[2 * i + 1] = __builtin_bit_cast(float, w[i] & 0xffff0000u); }
;         const u32x2 f = to_fp8x8(x); qa[ks] = (long)(((unsigned long long)f.y << 32) | f.x); }
;     const unsigned char* K8h = K8 + h * 128; const unsigned char* V8h = V8 + h * 128;
	v_bfe_u32 v115, v109, 16, 14
	v_lshl_add_u32 v115, v115, 7, v202
	v_and_b32_e32 v116, 0x3fff, v110
	v_lshl_add_u32 v116, v116, 7, v202
	v_bfe_u32 v117, v110, 16, 14
	v_lshl_add_u32 v117, v117, 7, v202
	v_and_b32_e32 v118, 0x3fff, v111
	v_lshl_add_u32 v118, v118, 7, v202
	v_bfe_u32 v119, v111, 16, 14
	v_lshl_add_u32 v119, v119, 7, v202
	v_lshrrev_b32_e32 v136, v227, v220
	v_lshrrev_b32_e32 v137, v227, v221
	v_lshrrev_b32_e32 v138, v227, v222
	v_lshrrev_b32_e32 v139, v227, v223
	v_and_b32_e32 v136, 0x3fff, v136
	v_and_b32_e32 v137, 0x3fff, v137
	v_and_b32_e32 v138, 0x3fff, v138
	v_and_b32_e32 v139, 0x3fff, v139
	v_lshlrev_b32_e32 v136, 7, v136
	v_lshlrev_b32_e32 v137, 7, v137
	v_lshlrev_b32_e32 v138, 7, v138
	v_lshlrev_b32_e32 v139, 7, v139
	v_lshlrev_b32_e32 v218, 16, v230
	v_and_b32_e32 v219, 0xffff0000, v230
	v_lshlrev_b32_e32 v246, 16, v231
	v_and_b32_e32 v247, 0xffff0000, v231
	v_cvt_pk_fp8_f32 v128, v218, v219
	s_nop 0
	v_cvt_pk_fp8_f32 v128, v246, v247 op_sel:[0,0,1]
	v_lshlrev_b32_e32 v218, 16, v232
	v_and_b32_e32 v219, 0xffff0000, v232
	v_lshlrev_b32_e32 v246, 16, v233
	v_and_b32_e32 v247, 0xffff0000, v233
	v_cvt_pk_fp8_f32 v129, v218, v219
	s_nop 0
	v_cvt_pk_fp8_f32 v129, v246, v247 op_sel:[0,0,1]
	v_lshlrev_b32_e32 v218, 16, v234
	v_and_b32_e32 v219, 0xffff0000, v234
	v_lshlrev_b32_e32 v246, 16, v235
	v_and_b32_e32 v247, 0xffff0000, v235
	v_cvt_pk_fp8_f32 v130, v218, v219
	s_nop 0
	v_cvt_pk_fp8_f32 v130, v246, v247 op_sel:[0,0,1]
	v_lshlrev_b32_e32 v218, 16, v236
	v_and_b32_e32 v219, 0xffff0000, v236
	v_lshlrev_b32_e32 v246, 16, v237
	v_and_b32_e32 v247, 0xffff0000, v237
	v_cvt_pk_fp8_f32 v131, v218, v219
	s_nop 0
	v_cvt_pk_fp8_f32 v131, v246, v247 op_sel:[0,0,1]
	v_lshlrev_b32_e32 v218, 16, v238
	v_and_b32_e32 v219, 0xffff0000, v238
	v_lshlrev_b32_e32 v246, 16, v239
	v_and_b32_e32 v247, 0xffff0000, v239
	v_cvt_pk_fp8_f32 v132, v218, v219
	s_nop 0
	v_cvt_pk_fp8_f32 v132, v246, v247 op_sel:[0,0,1]
	v_lshlrev_b32_e32 v218, 16, v240
	v_and_b32_e32 v219, 0xffff0000, v240
	v_lshlrev_b32_e32 v246, 16, v241
	v_and_b32_e32 v247, 0xffff0000, v241
	v_cvt_pk_fp8_f32 v133, v218, v219
	s_nop 0
	v_cvt_pk_fp8_f32 v133, v246, v247 op_sel:[0,0,1]
	v_lshlrev_b32_e32 v218, 16, v242
	v_and_b32_e32 v219, 0xffff0000, v242
	v_lshlrev_b32_e32 v246, 16, v243
	v_and_b32_e32 v247, 0xffff0000, v243
	v_cvt_pk_fp8_f32 v134, v218, v219
	s_nop 0
	v_cvt_pk_fp8_f32 v134, v246, v247 op_sel:[0,0,1]
	v_lshlrev_b32_e32 v218, 16, v244
	v_and_b32_e32 v219, 0xffff0000, v244
	v_lshlrev_b32_e32 v246, 16, v245
	v_and_b32_e32 v247, 0xffff0000, v245
	v_cvt_pk_fp8_f32 v135, v218, v219
	s_nop 0
	v_cvt_pk_fp8_f32 v135, v246, v247 op_sel:[0,0,1]
	s_add_i32 s49, s34, s48
	s_min_i32 s49, s49, 0x3fff
	s_lshl_b32 s0, s49, 9
	s_add_u32 s0, s38, s0
	s_addc_u32 s1, s39, 0
	s_mul_i32 s4, s49, 0x3c00
	s_add_u32 s4, s40, s4
	s_addc_u32 s5, s41, 0
	global_load_dwordx4 v[96:99], v200, s[0:1]
	global_load_dwordx4 v[100:103], v200, s[0:1] offset:16
	global_load_dwordx4 v[104:107], v200, s[0:1] offset:32
	global_load_dwordx4 v[108:111], v200, s[0:1] offset:48
	global_load_dwordx4 v[220:223], v216, s[0:1]
	global_load_dwordx4 v[230:233], v201, s[4:5]
	global_load_dwordx4 v[234:237], v201, s[4:5] offset:16
	global_load_dwordx4 v[238:241], v201, s[4:5] offset:128
	global_load_dwordx4 v[242:245], v201, s[4:5] offset:144
	s_waitcnt vmcnt(31)
	ds_write_b128 v224, v[0:3] offset:0
	ds_write_b128 v224, v[4:7] offset:1024
	ds_read_b128 v[144:147], v225 offset:0
	ds_read_b128 v[148:151], v226 offset:0
	global_load_dwordx4 v[0:3], v112, s[42:43]
	global_load_dwordx4 v[4:7], v113, s[42:43]
	s_waitcnt vmcnt(31)
	ds_write_b128 v224, v[8:11] offset:2048
	ds_write_b128 v224, v[12:15] offset:3072
	ds_read_b128 v[152:155], v225 offset:2048
	ds_read_b128 v[156:159], v226 offset:2048
	global_load_dwordx4 v[8:11], v114, s[42:43]
	global_load_dwordx4 v[12:15], v115, s[42:43]
	s_waitcnt lgkmcnt(4)
	v_mfma_f32_16x16x32_fp8_fp8 v[184:187], v[128:129], v[144:145], 0
	v_mfma_f32_16x16x32_fp8_fp8 v[184:187], v[130:131], v[146:147], v[184:187]
	v_mfma_f32_16x16x32_fp8_fp8 v[184:187], v[132:133], v[148:149], v[184:187]
	v_mfma_f32_16x16x32_fp8_fp8 v[184:187], v[134:135], v[150:151], v[184:187]
	s_waitcnt vmcnt(31)
	ds_write_b128 v224, v[16:19] offset:0
	ds_write_b128 v224, v[20:23] offset:1024
	ds_read_b128 v[144:147], v225 offset:0
	ds_read_b128 v[148:151], v226 offset:0
	global_load_dwordx4 v[16:19], v116, s[42:43]
	global_load_dwordx4 v[20:23], v117, s[42:43]
	s_waitcnt lgkmcnt(4)
	v_mfma_f32_16x16x32_fp8_fp8 v[188:191], v[128:129], v[152:153], 0
	v_mfma_f32_16x16x32_fp8_fp8 v[188:191], v[130:131], v[154:155], v[188:191]
	v_mfma_f32_16x16x32_fp8_fp8 v[188:191], v[132:133], v[156:157], v[188:191]
	v_mfma_f32_16x16x32_fp8_fp8 v[188:191], v[134:135], v[158:159], v[188:191]
	s_waitcnt vmcnt(31)
	ds_write_b128 v224, v[24:27] offset:2048
	ds_write_b128 v224, v[28:31] offset:3072
	ds_read_b128 v[152:155], v225 offset:2048
	ds_read_b128 v[156:159], v226 offset:2048
	global_load_dwordx4 v[24:27], v118, s[42:43]
	global_load_dwordx4 v[28:31], v119, s[42:43]
	s_waitcnt lgkmcnt(4)
	v_mfma_f32_16x16x32_fp8_fp8 v[192:195], v[128:129], v[144:145], 0
	v_mfma_f32_16x16x32_fp8_fp8 v[192:195], v[130:131], v[146:147], v[192:195]
	v_mfma_f32_16x16x32_fp8_fp8 v[192:195], v[132:133], v[148:149], v[192:195]
	v_mfma_f32_16x16x32_fp8_fp8 v[192:195], v[134:135], v[150:151], v[192:195]
	v_cndmask_b32_e64 v140, v140, v184, s[8:9]
	s_waitcnt vmcnt(31)
	ds_write_b128 v224, v[32:35] offset:0
	ds_write_b128 v224, v[36:39] offset:1024
	ds_read_b128 v[144:147], v225 offset:0
	ds_read_b128 v[148:151], v226 offset:0
	s_waitcnt lgkmcnt(4)
; __device__ __forceinline__ void sparse_unit7(const bf16_t* QKV, const unsigned char* K8, const unsigned char* V8, const int (&selv)[4], bf16_t* OB, LAS unsigned char* wl, int t, int h, int lane) {
;     ...
;             f32x4 acc[4];
; #pragma unroll
;             for (int g = 0; g < 4; ++g) { acc[g] = (f32x4){0.f, 0.f, 0.f, 0.f};
; #pragma unroll
;                 for (int ks = 0; ks < 4; ++ks) acc[g] = __builtin_amdgcn_mfma_f32_16x16x32_fp8_fp8(qa[ks], kf[g * 4 + ks], acc[g], 0, 0, 0); }
;             float sc = (slab == 0) ? acc[0][0] : (slab == 1) ? acc[1][0] : (slab == 2) ? acc[2][0] : acc[3][0];
	v_mfma_f32_16x16x32_fp8_fp8 v[196:199], v[128:129], v[152:153], 0
	v_mfma_f32_16x16x32_fp8_fp8 v[196:199], v[130:131], v[154:155], v[196:199]
	v_mfma_f32_16x16x32_fp8_fp8 v[196:199], v[132:133], v[156:157], v[196:199]
	v_mfma_f32_16x16x32_fp8_fp8 v[196:199], v[134:135], v[158:159], v[196:199]
	v_cndmask_b32_e64 v141, v141, v188, s[8:9]
	s_waitcnt vmcnt(29)
	ds_write_b128 v224, v[40:43] offset:2048
	ds_write_b128 v224, v[44:47] offset:3072
	ds_read_b128 v[152:155], v225 offset:2048
	ds_read_b128 v[156:159], v226 offset:2048
	s_waitcnt lgkmcnt(4)
	v_mfma_f32_16x16x32_fp8_fp8 v[184:187], v[128:129], v[144:145], 0
	v_mfma_f32_16x16x32_fp8_fp8 v[184:187], v[130:131], v[146:147], v[184:187]
	v_mfma_f32_16x16x32_fp8_fp8 v[184:187], v[132:133], v[148:149], v[184:187]
	v_mfma_f32_16x16x32_fp8_fp8 v[184:187], v[134:135], v[150:151], v[184:187]
	v_cndmask_b32_e64 v142, v142, v192, s[8:9]
	s_waitcnt vmcnt(27)
	ds_write_b128 v224, v[48:51] offset:0
	ds_write_b128 v224, v[52:55] offset:1024
	ds_read_b128 v[144:147], v225 offset:0
	ds_read_b128 v[148:151], v226 offset:0
	s_waitcnt lgkmcnt(4)
	v_mfma_f32_16x16x32_fp8_fp8 v[188:191], v[128:129], v[152:153], 0
	v_mfma_f32_16x16x32_fp8_fp8 v[188:191], v[130:131], v[154:155], v[188:191]
	v_mfma_f32_16x16x32_fp8_fp8 v[188:191], v[132:133], v[156:157], v[188:191]
	v_mfma_f32_16x16x32_fp8_fp8 v[188:191], v[134:135], v[158:159], v[188:191]
	v_cndmask_b32_e64 v143, v143, v196, s[8:9]
	s_waitcnt vmcnt(25)
	ds_write_b128 v224, v[56:59] offset:2048
	ds_write_b128 v224, v[60:63] offset:3072
	ds_read_b128 v[152:155], v225 offset:2048
	ds_read_b128 v[156:159], v226 offset:2048
	s_waitcnt lgkmcnt(4)
	v_mfma_f32_16x16x32_fp8_fp8 v[192:195], v[128:129], v[144:145], 0
	v_mfma_f32_16x16x32_fp8_fp8 v[192:195], v[130:131], v[146:147], v[192:195]
	v_mfma_f32_16x16x32_fp8_fp8 v[192:195], v[132:133], v[148:149], v[192:195]
	v_mfma_f32_16x16x32_fp8_fp8 v[192:195], v[134:135], v[150:151], v[192:195]
	v_cndmask_b32_e64 v140, v140, v184, s[10:11]
	s_waitcnt vmcnt(23)
	ds_write_b128 v224, v[64:67] offset:0
	ds_write_b128 v224, v[68:71] offset:1024
	ds_read_b128 v[144:147], v225 offset:0
	ds_read_b128 v[148:151], v226 offset:0
	s_waitcnt lgkmcnt(4)
	v_mfma_f32_16x16x32_fp8_fp8 v[196:199], v[128:129], v[152:153], 0
	v_mfma_f32_16x16x32_fp8_fp8 v[196:199], v[130:131], v[154:155], v[196:199]
	v_mfma_f32_16x16x32_fp8_fp8 v[196:199], v[132:133], v[156:157], v[196:199]
	v_mfma_f32_16x16x32_fp8_fp8 v[196:199], v[134:135], v[158:159], v[196:199]
	v_cndmask_b32_e64 v141, v141, v188, s[10:11]
	s_waitcnt vmcnt(21)
	ds_write_b128 v224, v[72:75] offset:2048
	ds_write_b128 v224, v[76:79] offset:3072
	ds_read_b128 v[152:155], v225 offset:2048
	ds_read_b128 v[156:159], v226 offset:2048
	s_waitcnt lgkmcnt(4)
	v_mfma_f32_16x16x32_fp8_fp8 v[184:187], v[128:129], v[144:145], 0
	v_mfma_f32_16x16x32_fp8_fp8 v[184:187], v[130:131], v[146:147], v[184:187]
	v_mfma_f32_16x16x32_fp8_fp8 v[184:187], v[132:133], v[148:149], v[184:187]
	v_mfma_f32_16x16x32_fp8_fp8 v[184:187], v[134:135], v[150:151], v[184:187]
	v_cndmask_b32_e64 v142, v142, v192, s[10:11]
	s_waitcnt vmcnt(19)
	ds_write_b128 v224, v[80:83] offset:0
	ds_write_b128 v224, v[84:87] offset:1024
	ds_read_b128 v[144:147], v225 offset:0
	ds_read_b128 v[148:151], v226 offset:0
	s_waitcnt lgkmcnt(4)
	v_mfma_f32_16x16x32_fp8_fp8 v[188:191], v[128:129], v[152:153], 0
	v_mfma_f32_16x16x32_fp8_fp8 v[188:191], v[130:131], v[154:155], v[188:191]
	v_mfma_f32_16x16x32_fp8_fp8 v[188:191], v[132:133], v[156:157], v[188:191]
	v_mfma_f32_16x16x32_fp8_fp8 v[188:191], v[134:135], v[158:159], v[188:191]
	v_cndmask_b32_e64 v143, v143, v196, s[10:11]
	s_waitcnt vmcnt(17)
	ds_write_b128 v224, v[88:91] offset:2048
	ds_write_b128 v224, v[92:95] offset:3072
	ds_read_b128 v[152:155], v225 offset:2048
	ds_read_b128 v[156:159], v226 offset:2048
	s_waitcnt lgkmcnt(4)
	v_mfma_f32_16x16x32_fp8_fp8 v[192:195], v[128:129], v[144:145], 0
	v_mfma_f32_16x16x32_fp8_fp8 v[192:195], v[130:131], v[146:147], v[192:195]
	v_mfma_f32_16x16x32_fp8_fp8 v[192:195], v[132:133], v[148:149], v[192:195]
	v_mfma_f32_16x16x32_fp8_fp8 v[192:195], v[134:135], v[150:151], v[192:195]
	v_cndmask_b32_e64 v140, v140, v184, s[16:17]
	s_waitcnt vmcnt(6)
	ds_write_b128 v224, v[0:3] offset:0
	ds_write_b128 v224, v[4:7] offset:1024
	ds_read_b128 v[144:147], v225 offset:0
	ds_read_b128 v[148:151], v226 offset:0
	s_waitcnt lgkmcnt(4)
	v_mfma_f32_16x16x32_fp8_fp8 v[196:199], v[128:129], v[152:153], 0
	v_mfma_f32_16x16x32_fp8_fp8 v[196:199], v[130:131], v[154:155], v[196:199]
	v_mfma_f32_16x16x32_fp8_fp8 v[196:199], v[132:133], v[156:157], v[196:199]
	v_mfma_f32_16x16x32_fp8_fp8 v[196:199], v[134:135], v[158:159], v[196:199]
	v_cndmask_b32_e64 v141, v141, v188, s[16:17]
	s_waitcnt vmcnt(4)
	ds_write_b128 v224, v[8:11] offset:2048
	ds_write_b128 v224, v[12:15] offset:3072
	ds_read_b128 v[152:155], v225 offset:2048
	ds_read_b128 v[156:159], v226 offset:2048
	s_waitcnt lgkmcnt(4)
	v_mfma_f32_16x16x32_fp8_fp8 v[184:187], v[128:129], v[144:145], 0
	v_mfma_f32_16x16x32_fp8_fp8 v[184:187], v[130:131], v[146:147], v[184:187]
	v_mfma_f32_16x16x32_fp8_fp8 v[184:187], v[132:133], v[148:149], v[184:187]
	v_mfma_f32_16x16x32_fp8_fp8 v[184:187], v[134:135], v[150:151], v[184:187]
	v_cndmask_b32_e64 v142, v142, v192, s[16:17]
	s_waitcnt vmcnt(2)
	ds_write_b128 v224, v[16:19] offset:0
	ds_write_b128 v224, v[20:23] offset:1024
	ds_read_b128 v[144:147], v225 offset:0
	ds_read_b128 v[148:151], v226 offset:0
	s_waitcnt lgkmcnt(4)
; __device__ __forceinline__ void sparse_unit7(const bf16_t* QKV, const unsigned char* K8, const unsigned char* V8, const int (&selv)[4], bf16_t* OB, LAS unsigned char* wl, int t, int h, int lane) {
;     ...
;             float sc = (slab == 0) ? acc[0][0] : (slab == 1) ? acc[1][0] : (slab == 2) ? acc[2][0] : acc[3][0];
;             sc = valid ? sc * 0.08838834764831845f : -INFINITY;
;             const float mn = fmaxf(m, wave_max(sc));
;             const float alpha = __expf(m - mn), p = __expf(sc - mn);
;             oa = oa * alpha; ob = ob * alpha; m = mn; l = l * alpha + p;
;             pt[lane] = p;
;             asm volatile("" ::: "memory");
;             const int sn_ = (s < 3) ? (s + 1) : 3;
;             s8_issue_k(kf, K8h, wsel, 64 * sn_, n16, slab);
;             s9_pv<0>(va, pt, half, oa, ob);
;             s9_issue_v<2>(va, V8h, ot, half, l4);
;             s9_pv<1>(vb, pt, half, oa, ob);
;             s9_issue_v<3>(vb, V8h, ot, half, l4);
;             s9_pv<2>(va, pt, half, oa, ob);
;             s9_issue_v<0>(va, V8h, otw + 64 * sn_, half, l4);
;             s9_pv<3>(vb, pt, half, oa, ob);
;         }
;     }
;     const float inv = 1.f / wave_sum(l);
	v_mfma_f32_16x16x32_fp8_fp8 v[188:191], v[128:129], v[152:153], 0
	v_mfma_f32_16x16x32_fp8_fp8 v[188:191], v[130:131], v[154:155], v[188:191]
	v_mfma_f32_16x16x32_fp8_fp8 v[188:191], v[132:133], v[156:157], v[188:191]
	v_mfma_f32_16x16x32_fp8_fp8 v[188:191], v[134:135], v[158:159], v[188:191]
	v_cndmask_b32_e64 v143, v143, v196, s[16:17]
	s_waitcnt vmcnt(0)
	ds_write_b128 v224, v[24:27] offset:2048
	ds_write_b128 v224, v[28:31] offset:3072
	ds_read_b128 v[152:155], v225 offset:2048
	ds_read_b128 v[156:159], v226 offset:2048
	s_waitcnt lgkmcnt(4)
	v_mfma_f32_16x16x32_fp8_fp8 v[192:195], v[128:129], v[144:145], 0
	v_mfma_f32_16x16x32_fp8_fp8 v[192:195], v[130:131], v[146:147], v[192:195]
	v_mfma_f32_16x16x32_fp8_fp8 v[192:195], v[132:133], v[148:149], v[192:195]
	v_mfma_f32_16x16x32_fp8_fp8 v[192:195], v[134:135], v[150:151], v[192:195]
	v_cndmask_b32_e64 v140, v140, v184, s[22:23]
	s_waitcnt lgkmcnt(0)
	v_mfma_f32_16x16x32_fp8_fp8 v[196:199], v[128:129], v[152:153], 0
	v_mfma_f32_16x16x32_fp8_fp8 v[196:199], v[130:131], v[154:155], v[196:199]
	v_mfma_f32_16x16x32_fp8_fp8 v[196:199], v[132:133], v[156:157], v[196:199]
	v_mfma_f32_16x16x32_fp8_fp8 v[196:199], v[134:135], v[158:159], v[196:199]
	v_cndmask_b32_e64 v141, v141, v188, s[22:23]
	s_nop 7
	v_cndmask_b32_e64 v142, v142, v192, s[22:23]
	s_nop 7
	v_cndmask_b32_e64 v143, v143, v196, s[22:23]
	s_sub_i32 s99, s98, 0
	v_mul_f32_e32 v140, 0x3db504f3, v140
	v_cmp_gt_i32_e32 vcc, s99, v217
	s_nop 1
	v_cndmask_b32_e32 v140, v208, v140, vcc
	s_sub_i32 s99, s98, 2
	v_mul_f32_e32 v141, 0x3db504f3, v141
	v_cmp_gt_i32_e32 vcc, s99, v217
	s_nop 1
	v_cndmask_b32_e32 v141, v208, v141, vcc
	s_sub_i32 s99, s98, 4
	v_mul_f32_e32 v142, 0x3db504f3, v142
	v_cmp_gt_i32_e32 vcc, s99, v217
	s_nop 1
	v_cndmask_b32_e32 v142, v208, v142, vcc
	s_sub_i32 s99, s98, 6
	v_mul_f32_e32 v143, 0x3db504f3, v143
	v_cmp_gt_i32_e32 vcc, s99, v217
	s_nop 1
	v_cndmask_b32_e32 v143, v208, v143, vcc
	v_max_f32_e32 v218, v140, v141
	v_max3_f32 v218, v218, v142, v143
	s_nop 1
	v_max_f32_dpp v218, v218, v218 row_ror:8 row_mask:0xf bank_mask:0xf bound_ctrl:1
	s_nop 1
	v_max_f32_dpp v218, v218, v218 row_ror:4 row_mask:0xf bank_mask:0xf bound_ctrl:1
	s_nop 1
	v_max_f32_dpp v218, v218, v218 quad_perm:[2,3,0,1] row_mask:0xf bank_mask:0xf bound_ctrl:1
	s_nop 1
	v_max_f32_dpp v218, v218, v218 quad_perm:[1,0,3,2] row_mask:0xf bank_mask:0xf bound_ctrl:1
	v_mov_b32_e32 v219, v218
	s_nop 1
	v_permlane16_swap_b32_e32 v218, v219
	s_nop 1
	v_max_f32_e32 v218, v218, v219
	v_mov_b32_e32 v219, v218
	s_nop 1
	v_permlane32_swap_b32_e32 v218, v219
	s_nop 1
	v_max_f32_e32 v218, v218, v219
	v_sub_f32_e32 v140, v140, v218
	v_sub_f32_e32 v141, v141, v218
	v_sub_f32_e32 v142, v142, v218
	v_sub_f32_e32 v143, v143, v218
	v_mul_f32_e32 v140, 0x3fb8aa3b, v140
	v_mul_f32_e32 v141, 0x3fb8aa3b, v141
	v_mul_f32_e32 v142, 0x3fb8aa3b, v142
	v_mul_f32_e32 v143, 0x3fb8aa3b, v143
	v_exp_f32_e32 v140, v140
	v_exp_f32_e32 v141, v141
	v_exp_f32_e32 v142, v142
	v_exp_f32_e32 v143, v143
	s_nop 1
	ds_write_b128 v213, v[140:143]
	ds_write_b128 v213, v[136:139] offset:1152
	v_add_f32_e32 v246, v140, v141
	v_add_f32_e32 v247, v142, v143
	v_add_f32_e32 v246, v246, v247
	ds_read_b128 v[64:67], v214 offset:1152
	ds_read_b128 v[68:71], v214 offset:1168
	ds_read_b128 v[72:75], v214 offset:1184
	ds_read_b128 v[76:79], v214 offset:1200
	ds_read_b128 v[80:83], v214 offset:1216
	ds_read_b128 v[84:87], v214 offset:1232
	ds_read_b128 v[88:91], v214 offset:1248
	ds_read_b128 v[92:95], v214 offset:1264
	ds_read_b128 v[112:115], v214 offset:0
	ds_read_b128 v[116:119], v214 offset:16
	ds_read_b128 v[120:123], v214 offset:32
	ds_read_b128 v[124:127], v214 offset:48
	v_mov_b32_e32 v144, 0
	v_mov_b32_e32 v145, 0
	v_mov_b32_e32 v146, 0
	v_mov_b32_e32 v147, 0
	v_mov_b32_e32 v148, 0
	v_mov_b32_e32 v149, 0
	v_mov_b32_e32 v150, 0
	v_mov_b32_e32 v151, 0
	v_mov_b32_e32 v152, 0
	v_mov_b32_e32 v153, 0
	v_mov_b32_e32 v154, 0
	v_mov_b32_e32 v155, 0
	v_mov_b32_e32 v156, 0
	v_mov_b32_e32 v157, 0
	v_mov_b32_e32 v158, 0
	v_mov_b32_e32 v159, 0
	s_waitcnt lgkmcnt(4)
	v_or_b32_e32 v218, v64, v203
	global_load_dwordx4 v[0:3], v218, s[44:45]
	v_or_b32_e32 v218, v65, v203
	global_load_dwordx4 v[4:7], v218, s[44:45]
	v_or_b32_e32 v218, v66, v203
	global_load_dwordx4 v[8:11], v218, s[44:45]
	v_or_b32_e32 v218, v67, v203
	global_load_dwordx4 v[12:15], v218, s[44:45]
	v_or_b32_e32 v218, v68, v203
	global_load_dwordx4 v[16:19], v218, s[44:45]
	v_or_b32_e32 v218, v69, v203
	global_load_dwordx4 v[20:23], v218, s[44:45]
	v_or_b32_e32 v218, v70, v203
	global_load_dwordx4 v[24:27], v218, s[44:45]
	v_or_b32_e32 v218, v71, v203
	global_load_dwordx4 v[28:31], v218, s[44:45]
	v_or_b32_e32 v218, v72, v203
	global_load_dwordx4 v[32:35], v218, s[44:45]
	v_or_b32_e32 v218, v73, v203
	global_load_dwordx4 v[36:39], v218, s[44:45]
	v_or_b32_e32 v218, v74, v203
	global_load_dwordx4 v[40:43], v218, s[44:45]
	v_or_b32_e32 v218, v75, v203
	global_load_dwordx4 v[44:47], v218, s[44:45]
	v_or_b32_e32 v218, v76, v203
	global_load_dwordx4 v[48:51], v218, s[44:45]
	v_or_b32_e32 v218, v77, v203
	global_load_dwordx4 v[52:55], v218, s[44:45]
	v_or_b32_e32 v218, v78, v203
	global_load_dwordx4 v[56:59], v218, s[44:45]
	v_or_b32_e32 v218, v79, v203
	global_load_dwordx4 v[60:63], v218, s[44:45]
	s_nop 1
	v_add_f32_dpp v246, v246, v246 row_ror:8 row_mask:0xf bank_mask:0xf bound_ctrl:1
	s_nop 1
	v_add_f32_dpp v246, v246, v246 row_ror:4 row_mask:0xf bank_mask:0xf bound_ctrl:1
	s_nop 1
	v_add_f32_dpp v246, v246, v246 quad_perm:[2,3,0,1] row_mask:0xf bank_mask:0xf bound_ctrl:1
	s_nop 1
	v_add_f32_dpp v246, v246, v246 quad_perm:[1,0,3,2] row_mask:0xf bank_mask:0xf bound_ctrl:1
	v_mov_b32_e32 v247, v246
	s_nop 1
	v_permlane16_swap_b32_e32 v246, v247
	s_nop 1
	v_add_f32_e32 v246, v246, v247
	v_mov_b32_e32 v247, v246
	s_nop 1
	v_permlane32_swap_b32_e32 v246, v247
	s_nop 1
	v_add_f32_e32 v246, v246, v247
	s_waitcnt lgkmcnt(0)
; #define LAS __attribute__((address_space(3)))
; template <int Q> __device__ __forceinline__ void s9_issue_v(unsigned (&vv)[8], const unsigned char* V8h, LAS const unsigned* otw, int half, int l4) {
; #pragma unroll
;     for (int u2 = 0; u2 < 8; ++u2) vv[u2] = *(const unsigned*)(V8h + (otw[2 * (Q * 8 + u2) + half] | (unsigned)l4));
; }
; template <int Q> __device__ __forceinline__ void s9_pv(const unsigned (&vv)[8], LAS const float* ptw, int half, f32x2_t& oa, f32x2_t& ob) {
; #pragma unroll
;     for (int u2 = 0; u2 < 8; ++u2) { const float p = ptw[2 * (Q * 8 + u2) + half];
;         oa = __builtin_amdgcn_cvt_pk_f32_fp8((int)vv[u2], false) * p + oa; ob = __builtin_amdgcn_cvt_pk_f32_fp8((int)vv[u2], true) * p + ob; }
; }
; __device__ __forceinline__ void sparse_unit7(const bf16_t* QKV, const unsigned char* K8, const unsigned char* V8, const int (&selv)[4], bf16_t* OB, LAS unsigned char* wl, int t, int h, int lane) {
;     ...
;             s9_pv<0>(va, pt, half, oa, ob);
;             s9_issue_v<2>(va, V8h, ot, half, l4);
;             s9_pv<1>(vb, pt, half, oa, ob);
;             s9_issue_v<3>(vb, V8h, ot, half, l4);
;             s9_pv<2>(va, pt, half, oa, ob);
;             s9_issue_v<0>(va, V8h, otw + 64 * sn_, half, l4);
;             s9_pv<3>(vb, pt, half, oa, ob);
	s_waitcnt vmcnt(15)
	v_cvt_pk_f32_fp8_e32 v[184:185], v0
	v_cvt_pk_f32_fp8_sdwa v[186:187], v0 src0_sel:WORD_1
	v_cvt_pk_f32_fp8_e32 v[188:189], v1
	v_cvt_pk_f32_fp8_sdwa v[190:191], v1 src0_sel:WORD_1
	v_cvt_pk_f32_fp8_e32 v[192:193], v2
	v_cvt_pk_f32_fp8_sdwa v[194:195], v2 src0_sel:WORD_1
	v_cvt_pk_f32_fp8_e32 v[196:197], v3
	v_cvt_pk_f32_fp8_sdwa v[198:199], v3 src0_sel:WORD_1
	v_or_b32_e32 v218, v80, v203
	global_load_dwordx4 v[0:3], v218, s[44:45]
	v_pk_fma_f32 v[144:145], v[184:185], v[112:113], v[144:145] op_sel_hi:[1,0,1]
	v_pk_fma_f32 v[146:147], v[186:187], v[112:113], v[146:147] op_sel_hi:[1,0,1]
	v_pk_fma_f32 v[148:149], v[188:189], v[112:113], v[148:149] op_sel_hi:[1,0,1]
	v_pk_fma_f32 v[150:151], v[190:191], v[112:113], v[150:151] op_sel_hi:[1,0,1]
	v_pk_fma_f32 v[152:153], v[192:193], v[112:113], v[152:153] op_sel_hi:[1,0,1]
	v_pk_fma_f32 v[154:155], v[194:195], v[112:113], v[154:155] op_sel_hi:[1,0,1]
	v_pk_fma_f32 v[156:157], v[196:197], v[112:113], v[156:157] op_sel_hi:[1,0,1]
	v_pk_fma_f32 v[158:159], v[198:199], v[112:113], v[158:159] op_sel_hi:[1,0,1]
	s_waitcnt vmcnt(15)
	v_cvt_pk_f32_fp8_e32 v[184:185], v4
	v_cvt_pk_f32_fp8_sdwa v[186:187], v4 src0_sel:WORD_1
	v_cvt_pk_f32_fp8_e32 v[188:189], v5
	v_cvt_pk_f32_fp8_sdwa v[190:191], v5 src0_sel:WORD_1
	v_cvt_pk_f32_fp8_e32 v[192:193], v6
	v_cvt_pk_f32_fp8_sdwa v[194:195], v6 src0_sel:WORD_1
	v_cvt_pk_f32_fp8_e32 v[196:197], v7
	v_cvt_pk_f32_fp8_sdwa v[198:199], v7 src0_sel:WORD_1
	v_or_b32_e32 v218, v81, v203
	global_load_dwordx4 v[4:7], v218, s[44:45]
	v_pk_fma_f32 v[144:145], v[184:185], v[112:113], v[144:145] op_sel:[0,1,0] op_sel_hi:[1,1,1]
	v_pk_fma_f32 v[146:147], v[186:187], v[112:113], v[146:147] op_sel:[0,1,0] op_sel_hi:[1,1,1]
	v_pk_fma_f32 v[148:149], v[188:189], v[112:113], v[148:149] op_sel:[0,1,0] op_sel_hi:[1,1,1]
	v_pk_fma_f32 v[150:151], v[190:191], v[112:113], v[150:151] op_sel:[0,1,0] op_sel_hi:[1,1,1]
	v_pk_fma_f32 v[152:153], v[192:193], v[112:113], v[152:153] op_sel:[0,1,0] op_sel_hi:[1,1,1]
	v_pk_fma_f32 v[154:155], v[194:195], v[112:113], v[154:155] op_sel:[0,1,0] op_sel_hi:[1,1,1]
	v_pk_fma_f32 v[156:157], v[196:197], v[112:113], v[156:157] op_sel:[0,1,0] op_sel_hi:[1,1,1]
	v_pk_fma_f32 v[158:159], v[198:199], v[112:113], v[158:159] op_sel:[0,1,0] op_sel_hi:[1,1,1]
	s_waitcnt vmcnt(15)
	v_cvt_pk_f32_fp8_e32 v[184:185], v8
	v_cvt_pk_f32_fp8_sdwa v[186:187], v8 src0_sel:WORD_1
	v_cvt_pk_f32_fp8_e32 v[188:189], v9
	v_cvt_pk_f32_fp8_sdwa v[190:191], v9 src0_sel:WORD_1
	v_cvt_pk_f32_fp8_e32 v[192:193], v10
	v_cvt_pk_f32_fp8_sdwa v[194:195], v10 src0_sel:WORD_1
	v_cvt_pk_f32_fp8_e32 v[196:197], v11
	v_cvt_pk_f32_fp8_sdwa v[198:199], v11 src0_sel:WORD_1
	v_or_b32_e32 v218, v82, v203
	global_load_dwordx4 v[8:11], v218, s[44:45]
	v_pk_fma_f32 v[144:145], v[184:185], v[114:115], v[144:145] op_sel_hi:[1,0,1]
	v_pk_fma_f32 v[146:147], v[186:187], v[114:115], v[146:147] op_sel_hi:[1,0,1]
	v_pk_fma_f32 v[148:149], v[188:189], v[114:115], v[148:149] op_sel_hi:[1,0,1]
	v_pk_fma_f32 v[150:151], v[190:191], v[114:115], v[150:151] op_sel_hi:[1,0,1]
	v_pk_fma_f32 v[152:153], v[192:193], v[114:115], v[152:153] op_sel_hi:[1,0,1]
	v_pk_fma_f32 v[154:155], v[194:195], v[114:115], v[154:155] op_sel_hi:[1,0,1]
	v_pk_fma_f32 v[156:157], v[196:197], v[114:115], v[156:157] op_sel_hi:[1,0,1]
	v_pk_fma_f32 v[158:159], v[198:199], v[114:115], v[158:159] op_sel_hi:[1,0,1]
	s_waitcnt vmcnt(15)
	v_cvt_pk_f32_fp8_e32 v[184:185], v12
	v_cvt_pk_f32_fp8_sdwa v[186:187], v12 src0_sel:WORD_1
	v_cvt_pk_f32_fp8_e32 v[188:189], v13
	v_cvt_pk_f32_fp8_sdwa v[190:191], v13 src0_sel:WORD_1
	v_cvt_pk_f32_fp8_e32 v[192:193], v14
	v_cvt_pk_f32_fp8_sdwa v[194:195], v14 src0_sel:WORD_1
	v_cvt_pk_f32_fp8_e32 v[196:197], v15
	v_cvt_pk_f32_fp8_sdwa v[198:199], v15 src0_sel:WORD_1
	v_or_b32_e32 v218, v83, v203
	global_load_dwordx4 v[12:15], v218, s[44:45]
	v_pk_fma_f32 v[144:145], v[184:185], v[114:115], v[144:145] op_sel:[0,1,0] op_sel_hi:[1,1,1]
	v_pk_fma_f32 v[146:147], v[186:187], v[114:115], v[146:147] op_sel:[0,1,0] op_sel_hi:[1,1,1]
	v_pk_fma_f32 v[148:149], v[188:189], v[114:115], v[148:149] op_sel:[0,1,0] op_sel_hi:[1,1,1]
	v_pk_fma_f32 v[150:151], v[190:191], v[114:115], v[150:151] op_sel:[0,1,0] op_sel_hi:[1,1,1]
	v_pk_fma_f32 v[152:153], v[192:193], v[114:115], v[152:153] op_sel:[0,1,0] op_sel_hi:[1,1,1]
	v_pk_fma_f32 v[154:155], v[194:195], v[114:115], v[154:155] op_sel:[0,1,0] op_sel_hi:[1,1,1]
	v_pk_fma_f32 v[156:157], v[196:197], v[114:115], v[156:157] op_sel:[0,1,0] op_sel_hi:[1,1,1]
	v_pk_fma_f32 v[158:159], v[198:199], v[114:115], v[158:159] op_sel:[0,1,0] op_sel_hi:[1,1,1]
	s_waitcnt vmcnt(15)
	v_cvt_pk_f32_fp8_e32 v[184:185], v16
	v_cvt_pk_f32_fp8_sdwa v[186:187], v16 src0_sel:WORD_1
	v_cvt_pk_f32_fp8_e32 v[188:189], v17
	v_cvt_pk_f32_fp8_sdwa v[190:191], v17 src0_sel:WORD_1
	v_cvt_pk_f32_fp8_e32 v[192:193], v18
	v_cvt_pk_f32_fp8_sdwa v[194:195], v18 src0_sel:WORD_1
	v_cvt_pk_f32_fp8_e32 v[196:197], v19
	v_cvt_pk_f32_fp8_sdwa v[198:199], v19 src0_sel:WORD_1
	v_or_b32_e32 v218, v84, v203
	global_load_dwordx4 v[16:19], v218, s[44:45]
	v_pk_fma_f32 v[144:145], v[184:185], v[116:117], v[144:145] op_sel_hi:[1,0,1]
	v_pk_fma_f32 v[146:147], v[186:187], v[116:117], v[146:147] op_sel_hi:[1,0,1]
	v_pk_fma_f32 v[148:149], v[188:189], v[116:117], v[148:149] op_sel_hi:[1,0,1]
	v_pk_fma_f32 v[150:151], v[190:191], v[116:117], v[150:151] op_sel_hi:[1,0,1]
	v_pk_fma_f32 v[152:153], v[192:193], v[116:117], v[152:153] op_sel_hi:[1,0,1]
	v_pk_fma_f32 v[154:155], v[194:195], v[116:117], v[154:155] op_sel_hi:[1,0,1]
	v_pk_fma_f32 v[156:157], v[196:197], v[116:117], v[156:157] op_sel_hi:[1,0,1]
	v_pk_fma_f32 v[158:159], v[198:199], v[116:117], v[158:159] op_sel_hi:[1,0,1]
	s_waitcnt vmcnt(15)
; #define LAS __attribute__((address_space(3)))
; template <int Q> __device__ __forceinline__ void s9_issue_v(unsigned (&vv)[8], const unsigned char* V8h, LAS const unsigned* otw, int half, int l4) {
; #pragma unroll
;     for (int u2 = 0; u2 < 8; ++u2) vv[u2] = *(const unsigned*)(V8h + (otw[2 * (Q * 8 + u2) + half] | (unsigned)l4));
; }
; template <int Q> __device__ __forceinline__ void s9_pv(const unsigned (&vv)[8], LAS const float* ptw, int half, f32x2_t& oa, f32x2_t& ob) {
; #pragma unroll
;     for (int u2 = 0; u2 < 8; ++u2) { const float p = ptw[2 * (Q * 8 + u2) + half];
;         oa = __builtin_amdgcn_cvt_pk_f32_fp8((int)vv[u2], false) * p + oa; ob = __builtin_amdgcn_cvt_pk_f32_fp8((int)vv[u2], true) * p + ob; }
; }
	v_cvt_pk_f32_fp8_e32 v[184:185], v20
	v_cvt_pk_f32_fp8_sdwa v[186:187], v20 src0_sel:WORD_1
	v_cvt_pk_f32_fp8_e32 v[188:189], v21
	v_cvt_pk_f32_fp8_sdwa v[190:191], v21 src0_sel:WORD_1
	v_cvt_pk_f32_fp8_e32 v[192:193], v22
	v_cvt_pk_f32_fp8_sdwa v[194:195], v22 src0_sel:WORD_1
	v_cvt_pk_f32_fp8_e32 v[196:197], v23
	v_cvt_pk_f32_fp8_sdwa v[198:199], v23 src0_sel:WORD_1
	v_or_b32_e32 v218, v85, v203
	global_load_dwordx4 v[20:23], v218, s[44:45]
	v_pk_fma_f32 v[144:145], v[184:185], v[116:117], v[144:145] op_sel:[0,1,0] op_sel_hi:[1,1,1]
	v_pk_fma_f32 v[146:147], v[186:187], v[116:117], v[146:147] op_sel:[0,1,0] op_sel_hi:[1,1,1]
	v_pk_fma_f32 v[148:149], v[188:189], v[116:117], v[148:149] op_sel:[0,1,0] op_sel_hi:[1,1,1]
	v_pk_fma_f32 v[150:151], v[190:191], v[116:117], v[150:151] op_sel:[0,1,0] op_sel_hi:[1,1,1]
	v_pk_fma_f32 v[152:153], v[192:193], v[116:117], v[152:153] op_sel:[0,1,0] op_sel_hi:[1,1,1]
	v_pk_fma_f32 v[154:155], v[194:195], v[116:117], v[154:155] op_sel:[0,1,0] op_sel_hi:[1,1,1]
	v_pk_fma_f32 v[156:157], v[196:197], v[116:117], v[156:157] op_sel:[0,1,0] op_sel_hi:[1,1,1]
	v_pk_fma_f32 v[158:159], v[198:199], v[116:117], v[158:159] op_sel:[0,1,0] op_sel_hi:[1,1,1]
	s_waitcnt vmcnt(15)
	v_cvt_pk_f32_fp8_e32 v[184:185], v24
	v_cvt_pk_f32_fp8_sdwa v[186:187], v24 src0_sel:WORD_1
	v_cvt_pk_f32_fp8_e32 v[188:189], v25
	v_cvt_pk_f32_fp8_sdwa v[190:191], v25 src0_sel:WORD_1
	v_cvt_pk_f32_fp8_e32 v[192:193], v26
	v_cvt_pk_f32_fp8_sdwa v[194:195], v26 src0_sel:WORD_1
	v_cvt_pk_f32_fp8_e32 v[196:197], v27
	v_cvt_pk_f32_fp8_sdwa v[198:199], v27 src0_sel:WORD_1
	v_or_b32_e32 v218, v86, v203
	global_load_dwordx4 v[24:27], v218, s[44:45]
	v_pk_fma_f32 v[144:145], v[184:185], v[118:119], v[144:145] op_sel_hi:[1,0,1]
	v_pk_fma_f32 v[146:147], v[186:187], v[118:119], v[146:147] op_sel_hi:[1,0,1]
	v_pk_fma_f32 v[148:149], v[188:189], v[118:119], v[148:149] op_sel_hi:[1,0,1]
	v_pk_fma_f32 v[150:151], v[190:191], v[118:119], v[150:151] op_sel_hi:[1,0,1]
	v_pk_fma_f32 v[152:153], v[192:193], v[118:119], v[152:153] op_sel_hi:[1,0,1]
	v_pk_fma_f32 v[154:155], v[194:195], v[118:119], v[154:155] op_sel_hi:[1,0,1]
	v_pk_fma_f32 v[156:157], v[196:197], v[118:119], v[156:157] op_sel_hi:[1,0,1]
	v_pk_fma_f32 v[158:159], v[198:199], v[118:119], v[158:159] op_sel_hi:[1,0,1]
	s_waitcnt vmcnt(15)
	v_cvt_pk_f32_fp8_e32 v[184:185], v28
	v_cvt_pk_f32_fp8_sdwa v[186:187], v28 src0_sel:WORD_1
	v_cvt_pk_f32_fp8_e32 v[188:189], v29
	v_cvt_pk_f32_fp8_sdwa v[190:191], v29 src0_sel:WORD_1
	v_cvt_pk_f32_fp8_e32 v[192:193], v30
	v_cvt_pk_f32_fp8_sdwa v[194:195], v30 src0_sel:WORD_1
	v_cvt_pk_f32_fp8_e32 v[196:197], v31
	v_cvt_pk_f32_fp8_sdwa v[198:199], v31 src0_sel:WORD_1
	v_or_b32_e32 v218, v87, v203
	global_load_dwordx4 v[28:31], v218, s[44:45]
	v_pk_fma_f32 v[144:145], v[184:185], v[118:119], v[144:145] op_sel:[0,1,0] op_sel_hi:[1,1,1]
	v_pk_fma_f32 v[146:147], v[186:187], v[118:119], v[146:147] op_sel:[0,1,0] op_sel_hi:[1,1,1]
	v_pk_fma_f32 v[148:149], v[188:189], v[118:119], v[148:149] op_sel:[0,1,0] op_sel_hi:[1,1,1]
	v_pk_fma_f32 v[150:151], v[190:191], v[118:119], v[150:151] op_sel:[0,1,0] op_sel_hi:[1,1,1]
	v_pk_fma_f32 v[152:153], v[192:193], v[118:119], v[152:153] op_sel:[0,1,0] op_sel_hi:[1,1,1]
	v_pk_fma_f32 v[154:155], v[194:195], v[118:119], v[154:155] op_sel:[0,1,0] op_sel_hi:[1,1,1]
	v_pk_fma_f32 v[156:157], v[196:197], v[118:119], v[156:157] op_sel:[0,1,0] op_sel_hi:[1,1,1]
	v_pk_fma_f32 v[158:159], v[198:199], v[118:119], v[158:159] op_sel:[0,1,0] op_sel_hi:[1,1,1]
	s_waitcnt vmcnt(15)
	v_cvt_pk_f32_fp8_e32 v[184:185], v32
	v_cvt_pk_f32_fp8_sdwa v[186:187], v32 src0_sel:WORD_1
	v_cvt_pk_f32_fp8_e32 v[188:189], v33
	v_cvt_pk_f32_fp8_sdwa v[190:191], v33 src0_sel:WORD_1
	v_cvt_pk_f32_fp8_e32 v[192:193], v34
	v_cvt_pk_f32_fp8_sdwa v[194:195], v34 src0_sel:WORD_1
	v_cvt_pk_f32_fp8_e32 v[196:197], v35
	v_cvt_pk_f32_fp8_sdwa v[198:199], v35 src0_sel:WORD_1
	v_or_b32_e32 v218, v88, v203
	global_load_dwordx4 v[32:35], v218, s[44:45]
	v_pk_fma_f32 v[144:145], v[184:185], v[120:121], v[144:145] op_sel_hi:[1,0,1]
	v_pk_fma_f32 v[146:147], v[186:187], v[120:121], v[146:147] op_sel_hi:[1,0,1]
	v_pk_fma_f32 v[148:149], v[188:189], v[120:121], v[148:149] op_sel_hi:[1,0,1]
	v_pk_fma_f32 v[150:151], v[190:191], v[120:121], v[150:151] op_sel_hi:[1,0,1]
	v_pk_fma_f32 v[152:153], v[192:193], v[120:121], v[152:153] op_sel_hi:[1,0,1]
	v_pk_fma_f32 v[154:155], v[194:195], v[120:121], v[154:155] op_sel_hi:[1,0,1]
	v_pk_fma_f32 v[156:157], v[196:197], v[120:121], v[156:157] op_sel_hi:[1,0,1]
	v_pk_fma_f32 v[158:159], v[198:199], v[120:121], v[158:159] op_sel_hi:[1,0,1]
	s_waitcnt vmcnt(15)
	v_cvt_pk_f32_fp8_e32 v[184:185], v36
	v_cvt_pk_f32_fp8_sdwa v[186:187], v36 src0_sel:WORD_1
	v_cvt_pk_f32_fp8_e32 v[188:189], v37
	v_cvt_pk_f32_fp8_sdwa v[190:191], v37 src0_sel:WORD_1
	v_cvt_pk_f32_fp8_e32 v[192:193], v38
	v_cvt_pk_f32_fp8_sdwa v[194:195], v38 src0_sel:WORD_1
	v_cvt_pk_f32_fp8_e32 v[196:197], v39
	v_cvt_pk_f32_fp8_sdwa v[198:199], v39 src0_sel:WORD_1
	v_or_b32_e32 v218, v89, v203
	global_load_dwordx4 v[36:39], v218, s[44:45]
	v_pk_fma_f32 v[144:145], v[184:185], v[120:121], v[144:145] op_sel:[0,1,0] op_sel_hi:[1,1,1]
	v_pk_fma_f32 v[146:147], v[186:187], v[120:121], v[146:147] op_sel:[0,1,0] op_sel_hi:[1,1,1]
	v_pk_fma_f32 v[148:149], v[188:189], v[120:121], v[148:149] op_sel:[0,1,0] op_sel_hi:[1,1,1]
	v_pk_fma_f32 v[150:151], v[190:191], v[120:121], v[150:151] op_sel:[0,1,0] op_sel_hi:[1,1,1]
	v_pk_fma_f32 v[152:153], v[192:193], v[120:121], v[152:153] op_sel:[0,1,0] op_sel_hi:[1,1,1]
	v_pk_fma_f32 v[154:155], v[194:195], v[120:121], v[154:155] op_sel:[0,1,0] op_sel_hi:[1,1,1]
	v_pk_fma_f32 v[156:157], v[196:197], v[120:121], v[156:157] op_sel:[0,1,0] op_sel_hi:[1,1,1]
	v_pk_fma_f32 v[158:159], v[198:199], v[120:121], v[158:159] op_sel:[0,1,0] op_sel_hi:[1,1,1]
	s_waitcnt vmcnt(15)
; #define LAS __attribute__((address_space(3)))
; template <int Q> __device__ __forceinline__ void s9_issue_v(unsigned (&vv)[8], const unsigned char* V8h, LAS const unsigned* otw, int half, int l4) {
; #pragma unroll
;     for (int u2 = 0; u2 < 8; ++u2) vv[u2] = *(const unsigned*)(V8h + (otw[2 * (Q * 8 + u2) + half] | (unsigned)l4));
; }
; template <int Q> __device__ __forceinline__ void s9_pv(const unsigned (&vv)[8], LAS const float* ptw, int half, f32x2_t& oa, f32x2_t& ob) {
; #pragma unroll
;     for (int u2 = 0; u2 < 8; ++u2) { const float p = ptw[2 * (Q * 8 + u2) + half];
;         oa = __builtin_amdgcn_cvt_pk_f32_fp8((int)vv[u2], false) * p + oa; ob = __builtin_amdgcn_cvt_pk_f32_fp8((int)vv[u2], true) * p + ob; }
; }
	v_cvt_pk_f32_fp8_e32 v[184:185], v40
	v_cvt_pk_f32_fp8_sdwa v[186:187], v40 src0_sel:WORD_1
	v_cvt_pk_f32_fp8_e32 v[188:189], v41
	v_cvt_pk_f32_fp8_sdwa v[190:191], v41 src0_sel:WORD_1
	v_cvt_pk_f32_fp8_e32 v[192:193], v42
	v_cvt_pk_f32_fp8_sdwa v[194:195], v42 src0_sel:WORD_1
	v_cvt_pk_f32_fp8_e32 v[196:197], v43
	v_cvt_pk_f32_fp8_sdwa v[198:199], v43 src0_sel:WORD_1
	v_or_b32_e32 v218, v90, v203
	global_load_dwordx4 v[40:43], v218, s[44:45]
	v_pk_fma_f32 v[144:145], v[184:185], v[122:123], v[144:145] op_sel_hi:[1,0,1]
	v_pk_fma_f32 v[146:147], v[186:187], v[122:123], v[146:147] op_sel_hi:[1,0,1]
	v_pk_fma_f32 v[148:149], v[188:189], v[122:123], v[148:149] op_sel_hi:[1,0,1]
	v_pk_fma_f32 v[150:151], v[190:191], v[122:123], v[150:151] op_sel_hi:[1,0,1]
	v_pk_fma_f32 v[152:153], v[192:193], v[122:123], v[152:153] op_sel_hi:[1,0,1]
	v_pk_fma_f32 v[154:155], v[194:195], v[122:123], v[154:155] op_sel_hi:[1,0,1]
	v_pk_fma_f32 v[156:157], v[196:197], v[122:123], v[156:157] op_sel_hi:[1,0,1]
	v_pk_fma_f32 v[158:159], v[198:199], v[122:123], v[158:159] op_sel_hi:[1,0,1]
	s_waitcnt vmcnt(15)
	v_cvt_pk_f32_fp8_e32 v[184:185], v44
	v_cvt_pk_f32_fp8_sdwa v[186:187], v44 src0_sel:WORD_1
	v_cvt_pk_f32_fp8_e32 v[188:189], v45
	v_cvt_pk_f32_fp8_sdwa v[190:191], v45 src0_sel:WORD_1
	v_cvt_pk_f32_fp8_e32 v[192:193], v46
	v_cvt_pk_f32_fp8_sdwa v[194:195], v46 src0_sel:WORD_1
	v_cvt_pk_f32_fp8_e32 v[196:197], v47
	v_cvt_pk_f32_fp8_sdwa v[198:199], v47 src0_sel:WORD_1
	v_or_b32_e32 v218, v91, v203
	global_load_dwordx4 v[44:47], v218, s[44:45]
	v_pk_fma_f32 v[144:145], v[184:185], v[122:123], v[144:145] op_sel:[0,1,0] op_sel_hi:[1,1,1]
	v_pk_fma_f32 v[146:147], v[186:187], v[122:123], v[146:147] op_sel:[0,1,0] op_sel_hi:[1,1,1]
	v_pk_fma_f32 v[148:149], v[188:189], v[122:123], v[148:149] op_sel:[0,1,0] op_sel_hi:[1,1,1]
	v_pk_fma_f32 v[150:151], v[190:191], v[122:123], v[150:151] op_sel:[0,1,0] op_sel_hi:[1,1,1]
	v_pk_fma_f32 v[152:153], v[192:193], v[122:123], v[152:153] op_sel:[0,1,0] op_sel_hi:[1,1,1]
	v_pk_fma_f32 v[154:155], v[194:195], v[122:123], v[154:155] op_sel:[0,1,0] op_sel_hi:[1,1,1]
	v_pk_fma_f32 v[156:157], v[196:197], v[122:123], v[156:157] op_sel:[0,1,0] op_sel_hi:[1,1,1]
	v_pk_fma_f32 v[158:159], v[198:199], v[122:123], v[158:159] op_sel:[0,1,0] op_sel_hi:[1,1,1]
	s_waitcnt vmcnt(15)
	v_cvt_pk_f32_fp8_e32 v[184:185], v48
	v_cvt_pk_f32_fp8_sdwa v[186:187], v48 src0_sel:WORD_1
	v_cvt_pk_f32_fp8_e32 v[188:189], v49
	v_cvt_pk_f32_fp8_sdwa v[190:191], v49 src0_sel:WORD_1
	v_cvt_pk_f32_fp8_e32 v[192:193], v50
	v_cvt_pk_f32_fp8_sdwa v[194:195], v50 src0_sel:WORD_1
	v_cvt_pk_f32_fp8_e32 v[196:197], v51
	v_cvt_pk_f32_fp8_sdwa v[198:199], v51 src0_sel:WORD_1
	v_or_b32_e32 v218, v92, v203
	global_load_dwordx4 v[48:51], v218, s[44:45]
	v_pk_fma_f32 v[144:145], v[184:185], v[124:125], v[144:145] op_sel_hi:[1,0,1]
	v_pk_fma_f32 v[146:147], v[186:187], v[124:125], v[146:147] op_sel_hi:[1,0,1]
	v_pk_fma_f32 v[148:149], v[188:189], v[124:125], v[148:149] op_sel_hi:[1,0,1]
	v_pk_fma_f32 v[150:151], v[190:191], v[124:125], v[150:151] op_sel_hi:[1,0,1]
	v_pk_fma_f32 v[152:153], v[192:193], v[124:125], v[152:153] op_sel_hi:[1,0,1]
	v_pk_fma_f32 v[154:155], v[194:195], v[124:125], v[154:155] op_sel_hi:[1,0,1]
	v_pk_fma_f32 v[156:157], v[196:197], v[124:125], v[156:157] op_sel_hi:[1,0,1]
	v_pk_fma_f32 v[158:159], v[198:199], v[124:125], v[158:159] op_sel_hi:[1,0,1]
	s_waitcnt vmcnt(15)
	v_cvt_pk_f32_fp8_e32 v[184:185], v52
	v_cvt_pk_f32_fp8_sdwa v[186:187], v52 src0_sel:WORD_1
	v_cvt_pk_f32_fp8_e32 v[188:189], v53
	v_cvt_pk_f32_fp8_sdwa v[190:191], v53 src0_sel:WORD_1
	v_cvt_pk_f32_fp8_e32 v[192:193], v54
	v_cvt_pk_f32_fp8_sdwa v[194:195], v54 src0_sel:WORD_1
	v_cvt_pk_f32_fp8_e32 v[196:197], v55
	v_cvt_pk_f32_fp8_sdwa v[198:199], v55 src0_sel:WORD_1
	v_or_b32_e32 v218, v93, v203
	global_load_dwordx4 v[52:55], v218, s[44:45]
	v_pk_fma_f32 v[144:145], v[184:185], v[124:125], v[144:145] op_sel:[0,1,0] op_sel_hi:[1,1,1]
	v_pk_fma_f32 v[146:147], v[186:187], v[124:125], v[146:147] op_sel:[0,1,0] op_sel_hi:[1,1,1]
	v_pk_fma_f32 v[148:149], v[188:189], v[124:125], v[148:149] op_sel:[0,1,0] op_sel_hi:[1,1,1]
	v_pk_fma_f32 v[150:151], v[190:191], v[124:125], v[150:151] op_sel:[0,1,0] op_sel_hi:[1,1,1]
	v_pk_fma_f32 v[152:153], v[192:193], v[124:125], v[152:153] op_sel:[0,1,0] op_sel_hi:[1,1,1]
	v_pk_fma_f32 v[154:155], v[194:195], v[124:125], v[154:155] op_sel:[0,1,0] op_sel_hi:[1,1,1]
	v_pk_fma_f32 v[156:157], v[196:197], v[124:125], v[156:157] op_sel:[0,1,0] op_sel_hi:[1,1,1]
	v_pk_fma_f32 v[158:159], v[198:199], v[124:125], v[158:159] op_sel:[0,1,0] op_sel_hi:[1,1,1]
	s_waitcnt vmcnt(15)
	v_cvt_pk_f32_fp8_e32 v[184:185], v56
	v_cvt_pk_f32_fp8_sdwa v[186:187], v56 src0_sel:WORD_1
	v_cvt_pk_f32_fp8_e32 v[188:189], v57
	v_cvt_pk_f32_fp8_sdwa v[190:191], v57 src0_sel:WORD_1
	v_cvt_pk_f32_fp8_e32 v[192:193], v58
	v_cvt_pk_f32_fp8_sdwa v[194:195], v58 src0_sel:WORD_1
	v_cvt_pk_f32_fp8_e32 v[196:197], v59
	v_cvt_pk_f32_fp8_sdwa v[198:199], v59 src0_sel:WORD_1
	v_or_b32_e32 v218, v94, v203
	global_load_dwordx4 v[56:59], v218, s[44:45]
	v_pk_fma_f32 v[144:145], v[184:185], v[126:127], v[144:145] op_sel_hi:[1,0,1]
	v_pk_fma_f32 v[146:147], v[186:187], v[126:127], v[146:147] op_sel_hi:[1,0,1]
	v_pk_fma_f32 v[148:149], v[188:189], v[126:127], v[148:149] op_sel_hi:[1,0,1]
	v_pk_fma_f32 v[150:151], v[190:191], v[126:127], v[150:151] op_sel_hi:[1,0,1]
	v_pk_fma_f32 v[152:153], v[192:193], v[126:127], v[152:153] op_sel_hi:[1,0,1]
	v_pk_fma_f32 v[154:155], v[194:195], v[126:127], v[154:155] op_sel_hi:[1,0,1]
	v_pk_fma_f32 v[156:157], v[196:197], v[126:127], v[156:157] op_sel_hi:[1,0,1]
	v_pk_fma_f32 v[158:159], v[198:199], v[126:127], v[158:159] op_sel_hi:[1,0,1]
	s_waitcnt vmcnt(15)
; #define LAS __attribute__((address_space(3)))
; template <int Q> __device__ __forceinline__ void s9_issue_v(unsigned (&vv)[8], const unsigned char* V8h, LAS const unsigned* otw, int half, int l4) {
; #pragma unroll
;     for (int u2 = 0; u2 < 8; ++u2) vv[u2] = *(const unsigned*)(V8h + (otw[2 * (Q * 8 + u2) + half] | (unsigned)l4));
; }
; template <int Q> __device__ __forceinline__ void s9_pv(const unsigned (&vv)[8], LAS const float* ptw, int half, f32x2_t& oa, f32x2_t& ob) {
; #pragma unroll
;     for (int u2 = 0; u2 < 8; ++u2) { const float p = ptw[2 * (Q * 8 + u2) + half];
;         oa = __builtin_amdgcn_cvt_pk_f32_fp8((int)vv[u2], false) * p + oa; ob = __builtin_amdgcn_cvt_pk_f32_fp8((int)vv[u2], true) * p + ob; }
; }
; __device__ __forceinline__ void sparse_unit7(const bf16_t* QKV, const unsigned char* K8, const unsigned char* V8, const int (&selv)[4], bf16_t* OB, LAS unsigned char* wl, int t, int h, int lane) {
;     ...
;             s9_pv<0>(va, pt, half, oa, ob);
;             s9_issue_v<2>(va, V8h, ot, half, l4);
;             s9_pv<1>(vb, pt, half, oa, ob);
;             s9_issue_v<3>(vb, V8h, ot, half, l4);
;             s9_pv<2>(va, pt, half, oa, ob);
;             s9_issue_v<0>(va, V8h, otw + 64 * sn_, half, l4);
;             s9_pv<3>(vb, pt, half, oa, ob);
	v_cvt_pk_f32_fp8_e32 v[184:185], v60
	v_cvt_pk_f32_fp8_sdwa v[186:187], v60 src0_sel:WORD_1
	v_cvt_pk_f32_fp8_e32 v[188:189], v61
	v_cvt_pk_f32_fp8_sdwa v[190:191], v61 src0_sel:WORD_1
	v_cvt_pk_f32_fp8_e32 v[192:193], v62
	v_cvt_pk_f32_fp8_sdwa v[194:195], v62 src0_sel:WORD_1
	v_cvt_pk_f32_fp8_e32 v[196:197], v63
	v_cvt_pk_f32_fp8_sdwa v[198:199], v63 src0_sel:WORD_1
	v_or_b32_e32 v218, v95, v203
	global_load_dwordx4 v[60:63], v218, s[44:45]
	v_pk_fma_f32 v[144:145], v[184:185], v[126:127], v[144:145] op_sel:[0,1,0] op_sel_hi:[1,1,1]
	v_pk_fma_f32 v[146:147], v[186:187], v[126:127], v[146:147] op_sel:[0,1,0] op_sel_hi:[1,1,1]
	v_pk_fma_f32 v[148:149], v[188:189], v[126:127], v[148:149] op_sel:[0,1,0] op_sel_hi:[1,1,1]
	v_pk_fma_f32 v[150:151], v[190:191], v[126:127], v[150:151] op_sel:[0,1,0] op_sel_hi:[1,1,1]
	v_pk_fma_f32 v[152:153], v[192:193], v[126:127], v[152:153] op_sel:[0,1,0] op_sel_hi:[1,1,1]
	v_pk_fma_f32 v[154:155], v[194:195], v[126:127], v[154:155] op_sel:[0,1,0] op_sel_hi:[1,1,1]
	v_pk_fma_f32 v[156:157], v[196:197], v[126:127], v[156:157] op_sel:[0,1,0] op_sel_hi:[1,1,1]
	v_pk_fma_f32 v[158:159], v[198:199], v[126:127], v[158:159] op_sel:[0,1,0] op_sel_hi:[1,1,1]
	ds_read_b128 v[112:115], v214 offset:64
	ds_read_b128 v[116:119], v214 offset:80
	ds_read_b128 v[120:123], v214 offset:96
	ds_read_b128 v[124:127], v214 offset:112
	s_waitcnt lgkmcnt(0)
	s_waitcnt vmcnt(15)
	v_cvt_pk_f32_fp8_e32 v[184:185], v0
	v_cvt_pk_f32_fp8_sdwa v[186:187], v0 src0_sel:WORD_1
	v_cvt_pk_f32_fp8_e32 v[188:189], v1
	v_cvt_pk_f32_fp8_sdwa v[190:191], v1 src0_sel:WORD_1
	v_cvt_pk_f32_fp8_e32 v[192:193], v2
	v_cvt_pk_f32_fp8_sdwa v[194:195], v2 src0_sel:WORD_1
	v_cvt_pk_f32_fp8_e32 v[196:197], v3
	v_cvt_pk_f32_fp8_sdwa v[198:199], v3 src0_sel:WORD_1
	v_pk_fma_f32 v[144:145], v[184:185], v[112:113], v[144:145] op_sel_hi:[1,0,1]
	v_pk_fma_f32 v[146:147], v[186:187], v[112:113], v[146:147] op_sel_hi:[1,0,1]
	v_pk_fma_f32 v[148:149], v[188:189], v[112:113], v[148:149] op_sel_hi:[1,0,1]
	v_pk_fma_f32 v[150:151], v[190:191], v[112:113], v[150:151] op_sel_hi:[1,0,1]
	v_pk_fma_f32 v[152:153], v[192:193], v[112:113], v[152:153] op_sel_hi:[1,0,1]
	v_pk_fma_f32 v[154:155], v[194:195], v[112:113], v[154:155] op_sel_hi:[1,0,1]
	v_pk_fma_f32 v[156:157], v[196:197], v[112:113], v[156:157] op_sel_hi:[1,0,1]
	v_pk_fma_f32 v[158:159], v[198:199], v[112:113], v[158:159] op_sel_hi:[1,0,1]
	s_waitcnt vmcnt(14)
	v_cvt_pk_f32_fp8_e32 v[184:185], v4
	v_cvt_pk_f32_fp8_sdwa v[186:187], v4 src0_sel:WORD_1
	v_cvt_pk_f32_fp8_e32 v[188:189], v5
	v_cvt_pk_f32_fp8_sdwa v[190:191], v5 src0_sel:WORD_1
	v_cvt_pk_f32_fp8_e32 v[192:193], v6
	v_cvt_pk_f32_fp8_sdwa v[194:195], v6 src0_sel:WORD_1
	v_cvt_pk_f32_fp8_e32 v[196:197], v7
	v_cvt_pk_f32_fp8_sdwa v[198:199], v7 src0_sel:WORD_1
	v_pk_fma_f32 v[144:145], v[184:185], v[112:113], v[144:145] op_sel:[0,1,0] op_sel_hi:[1,1,1]
	v_pk_fma_f32 v[146:147], v[186:187], v[112:113], v[146:147] op_sel:[0,1,0] op_sel_hi:[1,1,1]
	v_pk_fma_f32 v[148:149], v[188:189], v[112:113], v[148:149] op_sel:[0,1,0] op_sel_hi:[1,1,1]
	v_pk_fma_f32 v[150:151], v[190:191], v[112:113], v[150:151] op_sel:[0,1,0] op_sel_hi:[1,1,1]
	v_pk_fma_f32 v[152:153], v[192:193], v[112:113], v[152:153] op_sel:[0,1,0] op_sel_hi:[1,1,1]
	v_pk_fma_f32 v[154:155], v[194:195], v[112:113], v[154:155] op_sel:[0,1,0] op_sel_hi:[1,1,1]
	v_pk_fma_f32 v[156:157], v[196:197], v[112:113], v[156:157] op_sel:[0,1,0] op_sel_hi:[1,1,1]
	v_pk_fma_f32 v[158:159], v[198:199], v[112:113], v[158:159] op_sel:[0,1,0] op_sel_hi:[1,1,1]
	s_waitcnt vmcnt(13)
	v_cvt_pk_f32_fp8_e32 v[184:185], v8
	v_cvt_pk_f32_fp8_sdwa v[186:187], v8 src0_sel:WORD_1
	v_cvt_pk_f32_fp8_e32 v[188:189], v9
	v_cvt_pk_f32_fp8_sdwa v[190:191], v9 src0_sel:WORD_1
	v_cvt_pk_f32_fp8_e32 v[192:193], v10
	v_cvt_pk_f32_fp8_sdwa v[194:195], v10 src0_sel:WORD_1
	v_cvt_pk_f32_fp8_e32 v[196:197], v11
	v_cvt_pk_f32_fp8_sdwa v[198:199], v11 src0_sel:WORD_1
	v_pk_fma_f32 v[144:145], v[184:185], v[114:115], v[144:145] op_sel_hi:[1,0,1]
	v_pk_fma_f32 v[146:147], v[186:187], v[114:115], v[146:147] op_sel_hi:[1,0,1]
	v_pk_fma_f32 v[148:149], v[188:189], v[114:115], v[148:149] op_sel_hi:[1,0,1]
	v_pk_fma_f32 v[150:151], v[190:191], v[114:115], v[150:151] op_sel_hi:[1,0,1]
	v_pk_fma_f32 v[152:153], v[192:193], v[114:115], v[152:153] op_sel_hi:[1,0,1]
	v_pk_fma_f32 v[154:155], v[194:195], v[114:115], v[154:155] op_sel_hi:[1,0,1]
	v_pk_fma_f32 v[156:157], v[196:197], v[114:115], v[156:157] op_sel_hi:[1,0,1]
	v_pk_fma_f32 v[158:159], v[198:199], v[114:115], v[158:159] op_sel_hi:[1,0,1]
	s_waitcnt vmcnt(12)
	v_cvt_pk_f32_fp8_e32 v[184:185], v12
	v_cvt_pk_f32_fp8_sdwa v[186:187], v12 src0_sel:WORD_1
	v_cvt_pk_f32_fp8_e32 v[188:189], v13
	v_cvt_pk_f32_fp8_sdwa v[190:191], v13 src0_sel:WORD_1
	v_cvt_pk_f32_fp8_e32 v[192:193], v14
	v_cvt_pk_f32_fp8_sdwa v[194:195], v14 src0_sel:WORD_1
	v_cvt_pk_f32_fp8_e32 v[196:197], v15
	v_cvt_pk_f32_fp8_sdwa v[198:199], v15 src0_sel:WORD_1
	v_pk_fma_f32 v[144:145], v[184:185], v[114:115], v[144:145] op_sel:[0,1,0] op_sel_hi:[1,1,1]
	v_pk_fma_f32 v[146:147], v[186:187], v[114:115], v[146:147] op_sel:[0,1,0] op_sel_hi:[1,1,1]
	v_pk_fma_f32 v[148:149], v[188:189], v[114:115], v[148:149] op_sel:[0,1,0] op_sel_hi:[1,1,1]
	v_pk_fma_f32 v[150:151], v[190:191], v[114:115], v[150:151] op_sel:[0,1,0] op_sel_hi:[1,1,1]
	v_pk_fma_f32 v[152:153], v[192:193], v[114:115], v[152:153] op_sel:[0,1,0] op_sel_hi:[1,1,1]
	v_pk_fma_f32 v[154:155], v[194:195], v[114:115], v[154:155] op_sel:[0,1,0] op_sel_hi:[1,1,1]
	v_pk_fma_f32 v[156:157], v[196:197], v[114:115], v[156:157] op_sel:[0,1,0] op_sel_hi:[1,1,1]
	v_pk_fma_f32 v[158:159], v[198:199], v[114:115], v[158:159] op_sel:[0,1,0] op_sel_hi:[1,1,1]
	s_waitcnt vmcnt(11)
; #define LAS __attribute__((address_space(3)))
; template <int Q> __device__ __forceinline__ void s9_pv(const unsigned (&vv)[8], LAS const float* ptw, int half, f32x2_t& oa, f32x2_t& ob) {
; #pragma unroll
;     for (int u2 = 0; u2 < 8; ++u2) { const float p = ptw[2 * (Q * 8 + u2) + half];
;         oa = __builtin_amdgcn_cvt_pk_f32_fp8((int)vv[u2], false) * p + oa; ob = __builtin_amdgcn_cvt_pk_f32_fp8((int)vv[u2], true) * p + ob; }
; }
	v_cvt_pk_f32_fp8_e32 v[184:185], v16
	v_cvt_pk_f32_fp8_sdwa v[186:187], v16 src0_sel:WORD_1
	v_cvt_pk_f32_fp8_e32 v[188:189], v17
	v_cvt_pk_f32_fp8_sdwa v[190:191], v17 src0_sel:WORD_1
	v_cvt_pk_f32_fp8_e32 v[192:193], v18
	v_cvt_pk_f32_fp8_sdwa v[194:195], v18 src0_sel:WORD_1
	v_cvt_pk_f32_fp8_e32 v[196:197], v19
	v_cvt_pk_f32_fp8_sdwa v[198:199], v19 src0_sel:WORD_1
	v_pk_fma_f32 v[144:145], v[184:185], v[116:117], v[144:145] op_sel_hi:[1,0,1]
	v_pk_fma_f32 v[146:147], v[186:187], v[116:117], v[146:147] op_sel_hi:[1,0,1]
	v_pk_fma_f32 v[148:149], v[188:189], v[116:117], v[148:149] op_sel_hi:[1,0,1]
	v_pk_fma_f32 v[150:151], v[190:191], v[116:117], v[150:151] op_sel_hi:[1,0,1]
	v_pk_fma_f32 v[152:153], v[192:193], v[116:117], v[152:153] op_sel_hi:[1,0,1]
	v_pk_fma_f32 v[154:155], v[194:195], v[116:117], v[154:155] op_sel_hi:[1,0,1]
	v_pk_fma_f32 v[156:157], v[196:197], v[116:117], v[156:157] op_sel_hi:[1,0,1]
	v_pk_fma_f32 v[158:159], v[198:199], v[116:117], v[158:159] op_sel_hi:[1,0,1]
	s_waitcnt vmcnt(10)
	v_cvt_pk_f32_fp8_e32 v[184:185], v20
	v_cvt_pk_f32_fp8_sdwa v[186:187], v20 src0_sel:WORD_1
	v_cvt_pk_f32_fp8_e32 v[188:189], v21
	v_cvt_pk_f32_fp8_sdwa v[190:191], v21 src0_sel:WORD_1
	v_cvt_pk_f32_fp8_e32 v[192:193], v22
	v_cvt_pk_f32_fp8_sdwa v[194:195], v22 src0_sel:WORD_1
	v_cvt_pk_f32_fp8_e32 v[196:197], v23
	v_cvt_pk_f32_fp8_sdwa v[198:199], v23 src0_sel:WORD_1
	v_pk_fma_f32 v[144:145], v[184:185], v[116:117], v[144:145] op_sel:[0,1,0] op_sel_hi:[1,1,1]
	v_pk_fma_f32 v[146:147], v[186:187], v[116:117], v[146:147] op_sel:[0,1,0] op_sel_hi:[1,1,1]
	v_pk_fma_f32 v[148:149], v[188:189], v[116:117], v[148:149] op_sel:[0,1,0] op_sel_hi:[1,1,1]
	v_pk_fma_f32 v[150:151], v[190:191], v[116:117], v[150:151] op_sel:[0,1,0] op_sel_hi:[1,1,1]
	v_pk_fma_f32 v[152:153], v[192:193], v[116:117], v[152:153] op_sel:[0,1,0] op_sel_hi:[1,1,1]
	v_pk_fma_f32 v[154:155], v[194:195], v[116:117], v[154:155] op_sel:[0,1,0] op_sel_hi:[1,1,1]
	v_pk_fma_f32 v[156:157], v[196:197], v[116:117], v[156:157] op_sel:[0,1,0] op_sel_hi:[1,1,1]
	v_pk_fma_f32 v[158:159], v[198:199], v[116:117], v[158:159] op_sel:[0,1,0] op_sel_hi:[1,1,1]
	s_waitcnt vmcnt(9)
	v_cvt_pk_f32_fp8_e32 v[184:185], v24
	v_cvt_pk_f32_fp8_sdwa v[186:187], v24 src0_sel:WORD_1
	v_cvt_pk_f32_fp8_e32 v[188:189], v25
	v_cvt_pk_f32_fp8_sdwa v[190:191], v25 src0_sel:WORD_1
	v_cvt_pk_f32_fp8_e32 v[192:193], v26
	v_cvt_pk_f32_fp8_sdwa v[194:195], v26 src0_sel:WORD_1
	v_cvt_pk_f32_fp8_e32 v[196:197], v27
	v_cvt_pk_f32_fp8_sdwa v[198:199], v27 src0_sel:WORD_1
	v_pk_fma_f32 v[144:145], v[184:185], v[118:119], v[144:145] op_sel_hi:[1,0,1]
	v_pk_fma_f32 v[146:147], v[186:187], v[118:119], v[146:147] op_sel_hi:[1,0,1]
	v_pk_fma_f32 v[148:149], v[188:189], v[118:119], v[148:149] op_sel_hi:[1,0,1]
	v_pk_fma_f32 v[150:151], v[190:191], v[118:119], v[150:151] op_sel_hi:[1,0,1]
	v_pk_fma_f32 v[152:153], v[192:193], v[118:119], v[152:153] op_sel_hi:[1,0,1]
	v_pk_fma_f32 v[154:155], v[194:195], v[118:119], v[154:155] op_sel_hi:[1,0,1]
	v_pk_fma_f32 v[156:157], v[196:197], v[118:119], v[156:157] op_sel_hi:[1,0,1]
	v_pk_fma_f32 v[158:159], v[198:199], v[118:119], v[158:159] op_sel_hi:[1,0,1]
	s_waitcnt vmcnt(8)
	v_cvt_pk_f32_fp8_e32 v[184:185], v28
	v_cvt_pk_f32_fp8_sdwa v[186:187], v28 src0_sel:WORD_1
	v_cvt_pk_f32_fp8_e32 v[188:189], v29
	v_cvt_pk_f32_fp8_sdwa v[190:191], v29 src0_sel:WORD_1
	v_cvt_pk_f32_fp8_e32 v[192:193], v30
	v_cvt_pk_f32_fp8_sdwa v[194:195], v30 src0_sel:WORD_1
	v_cvt_pk_f32_fp8_e32 v[196:197], v31
	v_cvt_pk_f32_fp8_sdwa v[198:199], v31 src0_sel:WORD_1
	v_pk_fma_f32 v[144:145], v[184:185], v[118:119], v[144:145] op_sel:[0,1,0] op_sel_hi:[1,1,1]
	v_pk_fma_f32 v[146:147], v[186:187], v[118:119], v[146:147] op_sel:[0,1,0] op_sel_hi:[1,1,1]
	v_pk_fma_f32 v[148:149], v[188:189], v[118:119], v[148:149] op_sel:[0,1,0] op_sel_hi:[1,1,1]
	v_pk_fma_f32 v[150:151], v[190:191], v[118:119], v[150:151] op_sel:[0,1,0] op_sel_hi:[1,1,1]
	v_pk_fma_f32 v[152:153], v[192:193], v[118:119], v[152:153] op_sel:[0,1,0] op_sel_hi:[1,1,1]
	v_pk_fma_f32 v[154:155], v[194:195], v[118:119], v[154:155] op_sel:[0,1,0] op_sel_hi:[1,1,1]
	v_pk_fma_f32 v[156:157], v[196:197], v[118:119], v[156:157] op_sel:[0,1,0] op_sel_hi:[1,1,1]
	v_pk_fma_f32 v[158:159], v[198:199], v[118:119], v[158:159] op_sel:[0,1,0] op_sel_hi:[1,1,1]
	s_waitcnt vmcnt(7)
	v_cvt_pk_f32_fp8_e32 v[184:185], v32
	v_cvt_pk_f32_fp8_sdwa v[186:187], v32 src0_sel:WORD_1
	v_cvt_pk_f32_fp8_e32 v[188:189], v33
	v_cvt_pk_f32_fp8_sdwa v[190:191], v33 src0_sel:WORD_1
	v_cvt_pk_f32_fp8_e32 v[192:193], v34
	v_cvt_pk_f32_fp8_sdwa v[194:195], v34 src0_sel:WORD_1
	v_cvt_pk_f32_fp8_e32 v[196:197], v35
	v_cvt_pk_f32_fp8_sdwa v[198:199], v35 src0_sel:WORD_1
	v_pk_fma_f32 v[144:145], v[184:185], v[120:121], v[144:145] op_sel_hi:[1,0,1]
	v_pk_fma_f32 v[146:147], v[186:187], v[120:121], v[146:147] op_sel_hi:[1,0,1]
	v_pk_fma_f32 v[148:149], v[188:189], v[120:121], v[148:149] op_sel_hi:[1,0,1]
	v_pk_fma_f32 v[150:151], v[190:191], v[120:121], v[150:151] op_sel_hi:[1,0,1]
	v_pk_fma_f32 v[152:153], v[192:193], v[120:121], v[152:153] op_sel_hi:[1,0,1]
	v_pk_fma_f32 v[154:155], v[194:195], v[120:121], v[154:155] op_sel_hi:[1,0,1]
	v_pk_fma_f32 v[156:157], v[196:197], v[120:121], v[156:157] op_sel_hi:[1,0,1]
	v_pk_fma_f32 v[158:159], v[198:199], v[120:121], v[158:159] op_sel_hi:[1,0,1]
	s_waitcnt vmcnt(6)
; #define LAS __attribute__((address_space(3)))
; template <int Q> __device__ __forceinline__ void s9_pv(const unsigned (&vv)[8], LAS const float* ptw, int half, f32x2_t& oa, f32x2_t& ob) {
; #pragma unroll
;     for (int u2 = 0; u2 < 8; ++u2) { const float p = ptw[2 * (Q * 8 + u2) + half];
;         oa = __builtin_amdgcn_cvt_pk_f32_fp8((int)vv[u2], false) * p + oa; ob = __builtin_amdgcn_cvt_pk_f32_fp8((int)vv[u2], true) * p + ob; }
; }
	v_cvt_pk_f32_fp8_e32 v[184:185], v36
	v_cvt_pk_f32_fp8_sdwa v[186:187], v36 src0_sel:WORD_1
	v_cvt_pk_f32_fp8_e32 v[188:189], v37
	v_cvt_pk_f32_fp8_sdwa v[190:191], v37 src0_sel:WORD_1
	v_cvt_pk_f32_fp8_e32 v[192:193], v38
	v_cvt_pk_f32_fp8_sdwa v[194:195], v38 src0_sel:WORD_1
	v_cvt_pk_f32_fp8_e32 v[196:197], v39
	v_cvt_pk_f32_fp8_sdwa v[198:199], v39 src0_sel:WORD_1
	v_pk_fma_f32 v[144:145], v[184:185], v[120:121], v[144:145] op_sel:[0,1,0] op_sel_hi:[1,1,1]
	v_pk_fma_f32 v[146:147], v[186:187], v[120:121], v[146:147] op_sel:[0,1,0] op_sel_hi:[1,1,1]
	v_pk_fma_f32 v[148:149], v[188:189], v[120:121], v[148:149] op_sel:[0,1,0] op_sel_hi:[1,1,1]
	v_pk_fma_f32 v[150:151], v[190:191], v[120:121], v[150:151] op_sel:[0,1,0] op_sel_hi:[1,1,1]
	v_pk_fma_f32 v[152:153], v[192:193], v[120:121], v[152:153] op_sel:[0,1,0] op_sel_hi:[1,1,1]
	v_pk_fma_f32 v[154:155], v[194:195], v[120:121], v[154:155] op_sel:[0,1,0] op_sel_hi:[1,1,1]
	v_pk_fma_f32 v[156:157], v[196:197], v[120:121], v[156:157] op_sel:[0,1,0] op_sel_hi:[1,1,1]
	v_pk_fma_f32 v[158:159], v[198:199], v[120:121], v[158:159] op_sel:[0,1,0] op_sel_hi:[1,1,1]
	s_waitcnt vmcnt(5)
	v_cvt_pk_f32_fp8_e32 v[184:185], v40
	v_cvt_pk_f32_fp8_sdwa v[186:187], v40 src0_sel:WORD_1
	v_cvt_pk_f32_fp8_e32 v[188:189], v41
	v_cvt_pk_f32_fp8_sdwa v[190:191], v41 src0_sel:WORD_1
	v_cvt_pk_f32_fp8_e32 v[192:193], v42
	v_cvt_pk_f32_fp8_sdwa v[194:195], v42 src0_sel:WORD_1
	v_cvt_pk_f32_fp8_e32 v[196:197], v43
	v_cvt_pk_f32_fp8_sdwa v[198:199], v43 src0_sel:WORD_1
	v_pk_fma_f32 v[144:145], v[184:185], v[122:123], v[144:145] op_sel_hi:[1,0,1]
	v_pk_fma_f32 v[146:147], v[186:187], v[122:123], v[146:147] op_sel_hi:[1,0,1]
	v_pk_fma_f32 v[148:149], v[188:189], v[122:123], v[148:149] op_sel_hi:[1,0,1]
	v_pk_fma_f32 v[150:151], v[190:191], v[122:123], v[150:151] op_sel_hi:[1,0,1]
	v_pk_fma_f32 v[152:153], v[192:193], v[122:123], v[152:153] op_sel_hi:[1,0,1]
	v_pk_fma_f32 v[154:155], v[194:195], v[122:123], v[154:155] op_sel_hi:[1,0,1]
	v_pk_fma_f32 v[156:157], v[196:197], v[122:123], v[156:157] op_sel_hi:[1,0,1]
	v_pk_fma_f32 v[158:159], v[198:199], v[122:123], v[158:159] op_sel_hi:[1,0,1]
	s_waitcnt vmcnt(4)
	v_cvt_pk_f32_fp8_e32 v[184:185], v44
	v_cvt_pk_f32_fp8_sdwa v[186:187], v44 src0_sel:WORD_1
	v_cvt_pk_f32_fp8_e32 v[188:189], v45
	v_cvt_pk_f32_fp8_sdwa v[190:191], v45 src0_sel:WORD_1
	v_cvt_pk_f32_fp8_e32 v[192:193], v46
	v_cvt_pk_f32_fp8_sdwa v[194:195], v46 src0_sel:WORD_1
	v_cvt_pk_f32_fp8_e32 v[196:197], v47
	v_cvt_pk_f32_fp8_sdwa v[198:199], v47 src0_sel:WORD_1
	v_pk_fma_f32 v[144:145], v[184:185], v[122:123], v[144:145] op_sel:[0,1,0] op_sel_hi:[1,1,1]
	v_pk_fma_f32 v[146:147], v[186:187], v[122:123], v[146:147] op_sel:[0,1,0] op_sel_hi:[1,1,1]
	v_pk_fma_f32 v[148:149], v[188:189], v[122:123], v[148:149] op_sel:[0,1,0] op_sel_hi:[1,1,1]
	v_pk_fma_f32 v[150:151], v[190:191], v[122:123], v[150:151] op_sel:[0,1,0] op_sel_hi:[1,1,1]
	v_pk_fma_f32 v[152:153], v[192:193], v[122:123], v[152:153] op_sel:[0,1,0] op_sel_hi:[1,1,1]
	v_pk_fma_f32 v[154:155], v[194:195], v[122:123], v[154:155] op_sel:[0,1,0] op_sel_hi:[1,1,1]
	v_pk_fma_f32 v[156:157], v[196:197], v[122:123], v[156:157] op_sel:[0,1,0] op_sel_hi:[1,1,1]
	v_pk_fma_f32 v[158:159], v[198:199], v[122:123], v[158:159] op_sel:[0,1,0] op_sel_hi:[1,1,1]
	s_waitcnt vmcnt(3)
	v_cvt_pk_f32_fp8_e32 v[184:185], v48
	v_cvt_pk_f32_fp8_sdwa v[186:187], v48 src0_sel:WORD_1
	v_cvt_pk_f32_fp8_e32 v[188:189], v49
	v_cvt_pk_f32_fp8_sdwa v[190:191], v49 src0_sel:WORD_1
	v_cvt_pk_f32_fp8_e32 v[192:193], v50
	v_cvt_pk_f32_fp8_sdwa v[194:195], v50 src0_sel:WORD_1
	v_cvt_pk_f32_fp8_e32 v[196:197], v51
	v_cvt_pk_f32_fp8_sdwa v[198:199], v51 src0_sel:WORD_1
	v_pk_fma_f32 v[144:145], v[184:185], v[124:125], v[144:145] op_sel_hi:[1,0,1]
	v_pk_fma_f32 v[146:147], v[186:187], v[124:125], v[146:147] op_sel_hi:[1,0,1]
	v_pk_fma_f32 v[148:149], v[188:189], v[124:125], v[148:149] op_sel_hi:[1,0,1]
	v_pk_fma_f32 v[150:151], v[190:191], v[124:125], v[150:151] op_sel_hi:[1,0,1]
	v_pk_fma_f32 v[152:153], v[192:193], v[124:125], v[152:153] op_sel_hi:[1,0,1]
	v_pk_fma_f32 v[154:155], v[194:195], v[124:125], v[154:155] op_sel_hi:[1,0,1]
	v_pk_fma_f32 v[156:157], v[196:197], v[124:125], v[156:157] op_sel_hi:[1,0,1]
	v_pk_fma_f32 v[158:159], v[198:199], v[124:125], v[158:159] op_sel_hi:[1,0,1]
	s_waitcnt vmcnt(2)
	v_cvt_pk_f32_fp8_e32 v[184:185], v52
	v_cvt_pk_f32_fp8_sdwa v[186:187], v52 src0_sel:WORD_1
	v_cvt_pk_f32_fp8_e32 v[188:189], v53
	v_cvt_pk_f32_fp8_sdwa v[190:191], v53 src0_sel:WORD_1
	v_cvt_pk_f32_fp8_e32 v[192:193], v54
	v_cvt_pk_f32_fp8_sdwa v[194:195], v54 src0_sel:WORD_1
	v_cvt_pk_f32_fp8_e32 v[196:197], v55
	v_cvt_pk_f32_fp8_sdwa v[198:199], v55 src0_sel:WORD_1
	v_pk_fma_f32 v[144:145], v[184:185], v[124:125], v[144:145] op_sel:[0,1,0] op_sel_hi:[1,1,1]
	v_pk_fma_f32 v[146:147], v[186:187], v[124:125], v[146:147] op_sel:[0,1,0] op_sel_hi:[1,1,1]
	v_pk_fma_f32 v[148:149], v[188:189], v[124:125], v[148:149] op_sel:[0,1,0] op_sel_hi:[1,1,1]
	v_pk_fma_f32 v[150:151], v[190:191], v[124:125], v[150:151] op_sel:[0,1,0] op_sel_hi:[1,1,1]
	v_pk_fma_f32 v[152:153], v[192:193], v[124:125], v[152:153] op_sel:[0,1,0] op_sel_hi:[1,1,1]
	v_pk_fma_f32 v[154:155], v[194:195], v[124:125], v[154:155] op_sel:[0,1,0] op_sel_hi:[1,1,1]
	v_pk_fma_f32 v[156:157], v[196:197], v[124:125], v[156:157] op_sel:[0,1,0] op_sel_hi:[1,1,1]
	v_pk_fma_f32 v[158:159], v[198:199], v[124:125], v[158:159] op_sel:[0,1,0] op_sel_hi:[1,1,1]
	s_waitcnt vmcnt(1)
; __device__ __forceinline__ unsigned pk2(float lo, float hi) { return f2bf(lo) | (f2bf(hi) << 16); }
; __device__ __forceinline__ float swap32_sum(float a, float b) { unsigned x, y; pl32(__builtin_bit_cast(unsigned, a), __builtin_bit_cast(unsigned, b), x, y); return __builtin_bit_cast(float, x) + __builtin_bit_cast(float, y); }
; __device__ __forceinline__ void sparse_unit7(const bf16_t* QKV, const unsigned char* K8, const unsigned char* V8, const int (&selv)[4], bf16_t* OB, LAS unsigned char* wl, int t, int h, int lane) {
;     ...
;     const float inv = 1.f / wave_sum(l);
;     const float r0 = swap32_sum(oa.x, oa.x), r1 = swap32_sum(oa.y, oa.y), r2 = swap32_sum(ob.x, ob.x), r3 = swap32_sum(ob.y, ob.y);
;     if (half == 0) { u32x2 o; o.x = pk2(r0 * inv, r1 * inv); o.y = pk2(r2 * inv, r3 * inv); *(u32x2*)(OB + (size_t)t * 1024 + h * 128 + l4) = o; }
; __global__ void __launch_bounds__(NTHREADS, 2) mega(Args a) {
;     ...
;                     for (int t = qg; t < SEQ; t += nqg) { int selc[4];
; #pragma unroll
;                         for (int s = 0; s < 4; ++s) selc[s] = seln[s];
;                         const int tn = min(t + nqg, SEQ - 1);
; #pragma unroll
;                         for (int s = 0; s < 4; ++s) seln[s] = (int)SEL[(size_t)tn * 256 + 64 * s + lane];
;                         sparse_unit7(QKV, K8, V8, selc, OB, lds + wave * 4096, t, h, lane); } }
	v_cvt_pk_f32_fp8_e32 v[184:185], v56
	v_cvt_pk_f32_fp8_sdwa v[186:187], v56 src0_sel:WORD_1
	v_cvt_pk_f32_fp8_e32 v[188:189], v57
	v_cvt_pk_f32_fp8_sdwa v[190:191], v57 src0_sel:WORD_1
	v_cvt_pk_f32_fp8_e32 v[192:193], v58
	v_cvt_pk_f32_fp8_sdwa v[194:195], v58 src0_sel:WORD_1
	v_cvt_pk_f32_fp8_e32 v[196:197], v59
	v_cvt_pk_f32_fp8_sdwa v[198:199], v59 src0_sel:WORD_1
	v_pk_fma_f32 v[144:145], v[184:185], v[126:127], v[144:145] op_sel_hi:[1,0,1]
	v_pk_fma_f32 v[146:147], v[186:187], v[126:127], v[146:147] op_sel_hi:[1,0,1]
	v_pk_fma_f32 v[148:149], v[188:189], v[126:127], v[148:149] op_sel_hi:[1,0,1]
	v_pk_fma_f32 v[150:151], v[190:191], v[126:127], v[150:151] op_sel_hi:[1,0,1]
	v_pk_fma_f32 v[152:153], v[192:193], v[126:127], v[152:153] op_sel_hi:[1,0,1]
	v_pk_fma_f32 v[154:155], v[194:195], v[126:127], v[154:155] op_sel_hi:[1,0,1]
	v_pk_fma_f32 v[156:157], v[196:197], v[126:127], v[156:157] op_sel_hi:[1,0,1]
	v_pk_fma_f32 v[158:159], v[198:199], v[126:127], v[158:159] op_sel_hi:[1,0,1]
	s_waitcnt vmcnt(0)
	v_cvt_pk_f32_fp8_e32 v[184:185], v60
	v_cvt_pk_f32_fp8_sdwa v[186:187], v60 src0_sel:WORD_1
	v_cvt_pk_f32_fp8_e32 v[188:189], v61
	v_cvt_pk_f32_fp8_sdwa v[190:191], v61 src0_sel:WORD_1
	v_cvt_pk_f32_fp8_e32 v[192:193], v62
	v_cvt_pk_f32_fp8_sdwa v[194:195], v62 src0_sel:WORD_1
	v_cvt_pk_f32_fp8_e32 v[196:197], v63
	v_cvt_pk_f32_fp8_sdwa v[198:199], v63 src0_sel:WORD_1
	v_pk_fma_f32 v[144:145], v[184:185], v[126:127], v[144:145] op_sel:[0,1,0] op_sel_hi:[1,1,1]
	v_pk_fma_f32 v[146:147], v[186:187], v[126:127], v[146:147] op_sel:[0,1,0] op_sel_hi:[1,1,1]
	v_pk_fma_f32 v[148:149], v[188:189], v[126:127], v[148:149] op_sel:[0,1,0] op_sel_hi:[1,1,1]
	v_pk_fma_f32 v[150:151], v[190:191], v[126:127], v[150:151] op_sel:[0,1,0] op_sel_hi:[1,1,1]
	v_pk_fma_f32 v[152:153], v[192:193], v[126:127], v[152:153] op_sel:[0,1,0] op_sel_hi:[1,1,1]
	v_pk_fma_f32 v[154:155], v[194:195], v[126:127], v[154:155] op_sel:[0,1,0] op_sel_hi:[1,1,1]
	v_pk_fma_f32 v[156:157], v[196:197], v[126:127], v[156:157] op_sel:[0,1,0] op_sel_hi:[1,1,1]
	v_pk_fma_f32 v[158:159], v[198:199], v[126:127], v[158:159] op_sel:[0,1,0] op_sel_hi:[1,1,1]
	v_rcp_f32_e32 v218, v246
	s_nop 1
	v_fma_f32 v219, -v246, v218, 1.0
	v_fma_f32 v218, v219, v218, v218
	v_add_f32_dpp v144, v144, v144 row_ror:8 row_mask:0xf bank_mask:0xf bound_ctrl:1
	v_add_f32_dpp v145, v145, v145 row_ror:8 row_mask:0xf bank_mask:0xf bound_ctrl:1
	v_add_f32_dpp v146, v146, v146 row_ror:8 row_mask:0xf bank_mask:0xf bound_ctrl:1
	v_add_f32_dpp v147, v147, v147 row_ror:8 row_mask:0xf bank_mask:0xf bound_ctrl:1
	v_add_f32_dpp v148, v148, v148 row_ror:8 row_mask:0xf bank_mask:0xf bound_ctrl:1
	v_add_f32_dpp v149, v149, v149 row_ror:8 row_mask:0xf bank_mask:0xf bound_ctrl:1
	v_add_f32_dpp v150, v150, v150 row_ror:8 row_mask:0xf bank_mask:0xf bound_ctrl:1
	v_add_f32_dpp v151, v151, v151 row_ror:8 row_mask:0xf bank_mask:0xf bound_ctrl:1
	v_add_f32_dpp v152, v152, v152 row_ror:8 row_mask:0xf bank_mask:0xf bound_ctrl:1
	v_add_f32_dpp v153, v153, v153 row_ror:8 row_mask:0xf bank_mask:0xf bound_ctrl:1
	v_add_f32_dpp v154, v154, v154 row_ror:8 row_mask:0xf bank_mask:0xf bound_ctrl:1
	v_add_f32_dpp v155, v155, v155 row_ror:8 row_mask:0xf bank_mask:0xf bound_ctrl:1
	v_add_f32_dpp v156, v156, v156 row_ror:8 row_mask:0xf bank_mask:0xf bound_ctrl:1
	v_add_f32_dpp v157, v157, v157 row_ror:8 row_mask:0xf bank_mask:0xf bound_ctrl:1
	v_add_f32_dpp v158, v158, v158 row_ror:8 row_mask:0xf bank_mask:0xf bound_ctrl:1
	v_add_f32_dpp v159, v159, v159 row_ror:8 row_mask:0xf bank_mask:0xf bound_ctrl:1
	s_nop 1
	v_permlane16_swap_b32_e32 v144, v148
	v_permlane16_swap_b32_e32 v145, v149
	v_permlane16_swap_b32_e32 v146, v150
	v_permlane16_swap_b32_e32 v147, v151
	v_permlane16_swap_b32_e32 v152, v156
	v_permlane16_swap_b32_e32 v153, v157
	v_permlane16_swap_b32_e32 v154, v158
	v_permlane16_swap_b32_e32 v155, v159
	s_nop 1
	v_add_f32_e32 v144, v144, v148
	v_add_f32_e32 v145, v145, v149
	v_add_f32_e32 v146, v146, v150
	v_add_f32_e32 v147, v147, v151
	v_add_f32_e32 v152, v152, v156
	v_add_f32_e32 v153, v153, v157
	v_add_f32_e32 v154, v154, v158
	v_add_f32_e32 v155, v155, v159
	s_nop 1
	v_permlane32_swap_b32_e32 v144, v152
	v_permlane32_swap_b32_e32 v145, v153
	v_permlane32_swap_b32_e32 v146, v154
	v_permlane32_swap_b32_e32 v147, v155
	s_nop 1
	v_add_f32_e32 v144, v144, v152
	v_add_f32_e32 v145, v145, v153
	v_add_f32_e32 v146, v146, v154
	v_add_f32_e32 v147, v147, v155
	v_mul_f32_e32 v144, v144, v218
	v_mul_f32_e32 v145, v145, v218
	v_mul_f32_e32 v146, v146, v218
	v_mul_f32_e32 v147, v147, v218
	v_cvt_pk_bf16_f32 v246, v144, v145
	v_cvt_pk_bf16_f32 v247, v146, v147
	s_lshl_b32 s0, s34, 11
	s_add_u32 s0, s46, s0
	s_addc_u32 s1, s47, 0
	s_mov_b64 s[4:5], exec
	s_mov_b32 exec_lo, 0x00ff00ff
	s_mov_b32 exec_hi, 0x00ff00ff
	global_store_dwordx2 v215, v[246:247], s[0:1]
	s_mov_b64 exec, s[4:5]
	s_add_i32 s34, s34, s48
	s_cmpk_lt_i32 s34, 0x4000
	s_cbranch_scc1 .Lsp_unit
	s_waitcnt vmcnt(0)
	s_branch .LBB0_190
